# v9 plus hazard pads restored (s_nop after 128-bit stores in the transpose store phase, carry pads in split-K read-back)
# speedup vs baseline: 1.0077x; 1.0077x over previous
; #define LAS __attribute__((address_space(3)))
; __device__ __forceinline__ unsigned cvt_pk_bf16(float lo, float hi) { unsigned r; asm volatile("v_cvt_pk_bf16_f32 %0, %1, %2" : "=v"(r) : "v"(lo), "v"(hi)); return r; }
;     ...
;     const int c = lane & 7;
; #pragma unroll
;     for (int j = 0; j < 4; ++j) { const int n = (lane >> 3) + 8 * j; const LAS float* s = scr + (8 * c) * 33 + n;
;         u32x4 o; o.x = cvt_pk_bf16(s[0 * 33], s[1 * 33]); o.y = cvt_pk_bf16(s[2 * 33], s[3 * 33]); o.z = cvt_pk_bf16(s[4 * 33], s[5 * 33]); o.w = cvt_pk_bf16(s[6 * 33], s[7 * 33]);
;         const int nn = n0 + n; const int orow = mode ? ((nn >> 7) * 256 + (nn & 127) + (mode == 2 ? 128 : 0)) : nn;
;         *(u32x4*)(WT + (size_t)orow * K + k0 + 8 * c) = o; }
;     asm volatile("s_waitcnt lgkmcnt(0)" ::: "memory");
.LBB0_25:
	s_waitcnt lgkmcnt(0)
	ds_read2_b32 v[100:101], v30 offset1:33
	ds_read2_b32 v[102:103], v30 offset0:66 offset1:99
	ds_read2_b32 v[104:105], v30 offset0:132 offset1:165
	ds_read2_b32 v[106:107], v30 offset0:198 offset1:231
	ds_read2_b32 v[108:109], v30 offset0:8 offset1:41
	ds_read2_b32 v[110:111], v30 offset0:74 offset1:107
	ds_read2_b32 v[112:113], v30 offset0:140 offset1:173
	ds_read2_b32 v[114:115], v30 offset0:206 offset1:239
	ds_read2_b32 v[116:117], v30 offset0:16 offset1:49
	ds_read2_b32 v[118:119], v30 offset0:82 offset1:115
	ds_read2_b32 v[120:121], v30 offset0:148 offset1:181
	ds_read2_b32 v[122:123], v30 offset0:214 offset1:247
	ds_read2_b32 v[124:125], v30 offset0:24 offset1:57
	ds_read2_b32 v[126:127], v30 offset0:90 offset1:123
	ds_read2_b32 v[128:129], v30 offset0:156 offset1:189
	ds_read2_b32 v[130:131], v30 offset0:222 offset1:255
	s_waitcnt lgkmcnt(0)
	v_or_b32_e32 v16, s0, v3
	v_ashrrev_i32_e32 v17, 31, v16
	s_waitcnt lgkmcnt(0)
	v_cvt_pk_bf16_f32 v8, v100, v101
	v_lshl_add_u64 v[14:15], s[4:5], 1, v[4:5]
	v_lshlrev_b64 v[16:17], 12, v[16:17]
	s_waitcnt lgkmcnt(0)
	v_cvt_pk_bf16_f32 v9, v102, v103
	v_lshl_add_u64 v[16:17], v[14:15], 0, v[16:17]
	s_waitcnt lgkmcnt(0)
	v_cvt_pk_bf16_f32 v10, v104, v105
	s_waitcnt lgkmcnt(0)
	v_cvt_pk_bf16_f32 v11, v106, v107
	global_store_dwordx4 v[16:17], v[8:11], off
	s_nop 1
	v_or_b32_e32 v16, s0, v31
	s_waitcnt lgkmcnt(0)
	v_cvt_pk_bf16_f32 v8, v108, v109
	v_ashrrev_i32_e32 v17, 31, v16
	s_waitcnt lgkmcnt(0)
	v_cvt_pk_bf16_f32 v9, v110, v111
	v_lshlrev_b64 v[16:17], 12, v[16:17]
	s_waitcnt lgkmcnt(0)
	v_cvt_pk_bf16_f32 v10, v112, v113
	s_waitcnt lgkmcnt(0)
	v_cvt_pk_bf16_f32 v11, v114, v115
	v_lshl_add_u64 v[16:17], v[14:15], 0, v[16:17]
	global_store_dwordx4 v[16:17], v[8:11], off
	s_nop 1
	v_or_b32_e32 v16, s0, v32
	v_ashrrev_i32_e32 v17, 31, v16
	s_waitcnt lgkmcnt(0)
	v_cvt_pk_bf16_f32 v8, v116, v117
	s_waitcnt lgkmcnt(0)
	v_cvt_pk_bf16_f32 v9, v118, v119
	s_waitcnt lgkmcnt(0)
	v_cvt_pk_bf16_f32 v10, v120, v121
	v_lshlrev_b64 v[16:17], 12, v[16:17]
	s_waitcnt lgkmcnt(0)
	v_cvt_pk_bf16_f32 v11, v122, v123
	v_lshl_add_u64 v[16:17], v[14:15], 0, v[16:17]
	global_store_dwordx4 v[16:17], v[8:11], off
	s_nop 1
	s_add_i32 s12, s12, s21
	s_cmpk_lt_i32 s12, 0x1800
	s_waitcnt lgkmcnt(0)
	v_cvt_pk_bf16_f32 v8, v124, v125
	v_or_b32_e32 v12, s0, v33
	v_ashrrev_i32_e32 v13, 31, v12
	v_lshlrev_b64 v[12:13], 12, v[12:13]
	s_waitcnt lgkmcnt(0)
	v_cvt_pk_bf16_f32 v9, v126, v127
	v_lshl_add_u64 v[12:13], v[14:15], 0, v[12:13]
	s_waitcnt lgkmcnt(0)
	v_cvt_pk_bf16_f32 v10, v128, v129
	s_waitcnt lgkmcnt(0)
	v_cvt_pk_bf16_f32 v11, v130, v131
	global_store_dwordx4 v[12:13], v[8:11], off
	s_nop 1
	s_waitcnt lgkmcnt(0)
	s_cbranch_scc0 .LBB0_44

; #define LAS __attribute__((address_space(3)))
; __device__ __forceinline__ unsigned cvt_pk_bf16(float lo, float hi) { unsigned r; asm volatile("v_cvt_pk_bf16_f32 %0, %1, %2" : "=v"(r) : "v"(lo), "v"(hi)); return r; }
;     ...
;     const int c = lane & 7;
; #pragma unroll
;     for (int j = 0; j < 4; ++j) { const int n = (lane >> 3) + 8 * j; const LAS float* s = scr + (8 * c) * 33 + n;
;         u32x4 o; o.x = cvt_pk_bf16(s[0 * 33], s[1 * 33]); o.y = cvt_pk_bf16(s[2 * 33], s[3 * 33]); o.z = cvt_pk_bf16(s[4 * 33], s[5 * 33]); o.w = cvt_pk_bf16(s[6 * 33], s[7 * 33]);
;         const int nn = n0 + n; const int orow = mode ? ((nn >> 7) * 256 + (nn & 127) + (mode == 2 ? 128 : 0)) : nn;
;         *(u32x4*)(WT + (size_t)orow * K + k0 + 8 * c) = o; }
;     asm volatile("s_waitcnt lgkmcnt(0)" ::: "memory");
.LBB0_46:
	s_waitcnt lgkmcnt(0)
	ds_read2_b32 v[100:101], v19 offset1:33
	ds_read2_b32 v[102:103], v19 offset0:66 offset1:99
	ds_read2_b32 v[104:105], v19 offset0:132 offset1:165
	ds_read2_b32 v[106:107], v19 offset0:198 offset1:231
	ds_read2_b32 v[108:109], v19 offset0:8 offset1:41
	ds_read2_b32 v[110:111], v19 offset0:74 offset1:107
	ds_read2_b32 v[112:113], v19 offset0:140 offset1:173
	ds_read2_b32 v[114:115], v19 offset0:206 offset1:239
	ds_read2_b32 v[116:117], v19 offset0:16 offset1:49
	ds_read2_b32 v[118:119], v19 offset0:82 offset1:115
	ds_read2_b32 v[120:121], v19 offset0:148 offset1:181
	ds_read2_b32 v[122:123], v19 offset0:214 offset1:247
	ds_read2_b32 v[124:125], v19 offset0:24 offset1:57
	ds_read2_b32 v[126:127], v19 offset0:90 offset1:123
	ds_read2_b32 v[128:129], v19 offset0:156 offset1:189
	ds_read2_b32 v[130:131], v19 offset0:222 offset1:255
	s_waitcnt lgkmcnt(0)
	v_or_b32_e32 v34, s4, v3
	v_ashrrev_i32_e32 v35, 31, v34
	s_waitcnt lgkmcnt(0)
	v_cvt_pk_bf16_f32 v26, v100, v101
	v_lshl_add_u64 v[32:33], s[6:7], 1, v[12:13]
	v_lshlrev_b64 v[34:35], 12, v[34:35]
	s_waitcnt lgkmcnt(0)
	v_cvt_pk_bf16_f32 v27, v102, v103
	v_lshl_add_u64 v[34:35], v[32:33], 0, v[34:35]
	s_waitcnt lgkmcnt(0)
	v_cvt_pk_bf16_f32 v28, v104, v105
	s_waitcnt lgkmcnt(0)
	v_cvt_pk_bf16_f32 v29, v106, v107
	global_store_dwordx4 v[34:35], v[26:29], off
	s_nop 1
	v_or_b32_e32 v34, s4, v49
	v_ashrrev_i32_e32 v35, 31, v34
	s_waitcnt lgkmcnt(0)
	v_cvt_pk_bf16_f32 v26, v108, v109
	v_lshlrev_b64 v[34:35], 12, v[34:35]
	s_waitcnt lgkmcnt(0)
	v_cvt_pk_bf16_f32 v27, v110, v111
	v_lshl_add_u64 v[34:35], v[32:33], 0, v[34:35]
	s_waitcnt lgkmcnt(0)
	v_cvt_pk_bf16_f32 v28, v112, v113
	s_waitcnt lgkmcnt(0)
	v_cvt_pk_bf16_f32 v29, v114, v115
	global_store_dwordx4 v[34:35], v[26:29], off
	s_nop 1
	v_or_b32_e32 v34, s4, v50
	s_waitcnt lgkmcnt(0)
	v_cvt_pk_bf16_f32 v26, v116, v117
	v_ashrrev_i32_e32 v35, 31, v34
	s_waitcnt lgkmcnt(0)
	v_cvt_pk_bf16_f32 v27, v118, v119
	v_lshlrev_b64 v[34:35], 12, v[34:35]
	s_waitcnt lgkmcnt(0)
	v_cvt_pk_bf16_f32 v28, v120, v121
	s_waitcnt lgkmcnt(0)
	v_cvt_pk_bf16_f32 v29, v122, v123
	v_lshl_add_u64 v[34:35], v[32:33], 0, v[34:35]
	global_store_dwordx4 v[34:35], v[26:29], off
	s_nop 1
	v_or_b32_e32 v34, s4, v51
	v_ashrrev_i32_e32 v35, 31, v34
	s_waitcnt lgkmcnt(0)
	v_cvt_pk_bf16_f32 v26, v124, v125
	s_waitcnt lgkmcnt(0)
	v_cvt_pk_bf16_f32 v27, v126, v127
	s_waitcnt lgkmcnt(0)
	v_cvt_pk_bf16_f32 v28, v128, v129
	v_lshlrev_b64 v[34:35], 12, v[34:35]
	s_waitcnt lgkmcnt(0)
	v_cvt_pk_bf16_f32 v29, v130, v131
	v_lshl_add_u64 v[30:31], v[32:33], 0, v[34:35]
	global_store_dwordx4 v[30:31], v[26:29], off
	s_nop 1
	s_waitcnt lgkmcnt(0)

;     ...
;     for (int i = 0; i < 32; ++i) { const int kk = 2 * i + (lane >> 5); float v = __builtin_nontemporal_load(W + (size_t)(k0 + kk) * N + n0 + (lane & 31)); if (gain) v *= gain[k0 + kk]; scr[kk * 33 + (lane & 31)] = v; }
.LBB0_53:
	v_lshl_add_u64 v[164:165], v[40:41], 0, s[4:5]
	global_load_dword v100, v[164:165], off nt
	v_lshl_add_u64 v[164:165], v[38:39], 0, s[4:5]
	global_load_dword v101, v[164:165], off nt
	v_lshl_add_u64 v[164:165], v[36:37], 0, s[4:5]
	global_load_dword v102, v[164:165], off nt
	v_lshl_add_u64 v[164:165], v[34:35], 0, s[4:5]
	global_load_dword v103, v[164:165], off nt
	v_lshl_add_u64 v[164:165], v[32:33], 0, s[4:5]
	global_load_dword v104, v[164:165], off nt
	v_lshl_add_u64 v[164:165], v[30:31], 0, s[4:5]
	global_load_dword v105, v[164:165], off nt
	v_lshl_add_u64 v[164:165], v[28:29], 0, s[4:5]
	global_load_dword v106, v[164:165], off nt
	v_lshl_add_u64 v[164:165], v[26:27], 0, s[4:5]
	global_load_dword v107, v[164:165], off nt
	s_add_u32 s4, s4, 0x20000
	s_addc_u32 s5, s5, 0
	v_lshl_add_u64 v[164:165], v[40:41], 0, s[4:5]
	global_load_dword v108, v[164:165], off nt
	v_lshl_add_u64 v[164:165], v[38:39], 0, s[4:5]
	global_load_dword v109, v[164:165], off nt
	v_lshl_add_u64 v[164:165], v[36:37], 0, s[4:5]
	global_load_dword v110, v[164:165], off nt
	v_lshl_add_u64 v[164:165], v[34:35], 0, s[4:5]
	global_load_dword v111, v[164:165], off nt
	v_lshl_add_u64 v[164:165], v[32:33], 0, s[4:5]
	global_load_dword v112, v[164:165], off nt
	v_lshl_add_u64 v[164:165], v[30:31], 0, s[4:5]
	global_load_dword v113, v[164:165], off nt
	v_lshl_add_u64 v[164:165], v[28:29], 0, s[4:5]
	global_load_dword v114, v[164:165], off nt
	v_lshl_add_u64 v[164:165], v[26:27], 0, s[4:5]
	global_load_dword v115, v[164:165], off nt
	s_add_u32 s4, s4, 0x20000
	s_addc_u32 s5, s5, 0
	v_lshl_add_u64 v[164:165], v[40:41], 0, s[4:5]
	global_load_dword v116, v[164:165], off nt
	v_lshl_add_u64 v[164:165], v[38:39], 0, s[4:5]
	global_load_dword v117, v[164:165], off nt
	v_lshl_add_u64 v[164:165], v[36:37], 0, s[4:5]
	global_load_dword v118, v[164:165], off nt
	v_lshl_add_u64 v[164:165], v[34:35], 0, s[4:5]
	global_load_dword v119, v[164:165], off nt
	v_lshl_add_u64 v[164:165], v[32:33], 0, s[4:5]
	global_load_dword v120, v[164:165], off nt
	v_lshl_add_u64 v[164:165], v[30:31], 0, s[4:5]
	global_load_dword v121, v[164:165], off nt
	v_lshl_add_u64 v[164:165], v[28:29], 0, s[4:5]
	global_load_dword v122, v[164:165], off nt
	v_lshl_add_u64 v[164:165], v[26:27], 0, s[4:5]
	global_load_dword v123, v[164:165], off nt
	s_add_u32 s4, s4, 0x20000
	s_addc_u32 s5, s5, 0
	v_lshl_add_u64 v[164:165], v[40:41], 0, s[4:5]
	global_load_dword v124, v[164:165], off nt
	v_lshl_add_u64 v[164:165], v[38:39], 0, s[4:5]
	global_load_dword v125, v[164:165], off nt
	v_lshl_add_u64 v[164:165], v[36:37], 0, s[4:5]
	global_load_dword v126, v[164:165], off nt
	v_lshl_add_u64 v[164:165], v[34:35], 0, s[4:5]
	global_load_dword v127, v[164:165], off nt
	v_lshl_add_u64 v[164:165], v[32:33], 0, s[4:5]
	global_load_dword v128, v[164:165], off nt
	v_lshl_add_u64 v[164:165], v[30:31], 0, s[4:5]
	global_load_dword v129, v[164:165], off nt
	v_lshl_add_u64 v[164:165], v[28:29], 0, s[4:5]
	global_load_dword v130, v[164:165], off nt
	v_lshl_add_u64 v[164:165], v[26:27], 0, s[4:5]
	global_load_dword v131, v[164:165], off nt
	s_add_u32 s4, s4, 0x20000
	s_addc_u32 s5, s5, 0
	s_waitcnt vmcnt(24)
	ds_write_b32 v4, v100
	ds_write_b32 v4, v101 offset:264
	ds_write_b32 v4, v102 offset:528
	ds_write_b32 v4, v103 offset:792
	ds_write_b32 v4, v104 offset:1056
	ds_write_b32 v4, v105 offset:1320
	ds_write_b32 v4, v106 offset:1584
	ds_write_b32 v4, v107 offset:1848
	s_waitcnt vmcnt(16)
; #define LAS __attribute__((address_space(3)))
; __device__ __forceinline__ unsigned cvt_pk_bf16(float lo, float hi) { unsigned r; asm volatile("v_cvt_pk_bf16_f32 %0, %1, %2" : "=v"(r) : "v"(lo), "v"(hi)); return r; }
;     ...
;     for (int i = 0; i < 32; ++i) { const int kk = 2 * i + (lane >> 5); float v = __builtin_nontemporal_load(W + (size_t)(k0 + kk) * N + n0 + (lane & 31)); if (gain) v *= gain[k0 + kk]; scr[kk * 33 + (lane & 31)] = v; }
;     asm volatile("s_waitcnt lgkmcnt(0)" ::: "memory");
;     const int c = lane & 7;
; #pragma unroll
;     for (int j = 0; j < 4; ++j) { const int n = (lane >> 3) + 8 * j; const LAS float* s = scr + (8 * c) * 33 + n;
;         u32x4 o; o.x = cvt_pk_bf16(s[0 * 33], s[1 * 33]); o.y = cvt_pk_bf16(s[2 * 33], s[3 * 33]); o.z = cvt_pk_bf16(s[4 * 33], s[5 * 33]); o.w = cvt_pk_bf16(s[6 * 33], s[7 * 33]);
;         const int nn = n0 + n; const int orow = mode ? ((nn >> 7) * 256 + (nn & 127) + (mode == 2 ? 128 : 0)) : nn;
;         *(u32x4*)(WT + (size_t)orow * K + k0 + 8 * c) = o; }
;     asm volatile("s_waitcnt lgkmcnt(0)" ::: "memory");
	ds_write_b32 v4, v108 offset:2112
	ds_write_b32 v4, v109 offset:2376
	ds_write_b32 v4, v110 offset:2640
	ds_write_b32 v4, v111 offset:2904
	ds_write_b32 v4, v112 offset:3168
	ds_write_b32 v4, v113 offset:3432
	ds_write_b32 v4, v114 offset:3696
	ds_write_b32 v4, v115 offset:3960
	s_waitcnt vmcnt(8)
	ds_write_b32 v4, v116 offset:4224
	ds_write_b32 v4, v117 offset:4488
	ds_write_b32 v4, v118 offset:4752
	ds_write_b32 v4, v119 offset:5016
	ds_write_b32 v4, v120 offset:5280
	ds_write_b32 v4, v121 offset:5544
	ds_write_b32 v4, v122 offset:5808
	ds_write_b32 v4, v123 offset:6072
	s_waitcnt vmcnt(0)
	ds_write_b32 v4, v124 offset:6336
	ds_write_b32 v4, v125 offset:6600
	ds_write_b32 v4, v126 offset:6864
	ds_write_b32 v4, v127 offset:7128
	ds_write_b32 v4, v128 offset:7392
	ds_write_b32 v4, v129 offset:7656
	ds_write_b32 v4, v130 offset:7920
	ds_write_b32 v4, v131 offset:8184
	v_add_u32_e32 v4, 0x2100, v4
	s_lshl_b32 s4, s3, 5
	s_waitcnt lgkmcnt(0)
	ds_read2_b32 v[100:101], v19 offset1:33
	ds_read2_b32 v[102:103], v19 offset0:66 offset1:99
	ds_read2_b32 v[104:105], v19 offset0:132 offset1:165
	ds_read2_b32 v[106:107], v19 offset0:198 offset1:231
	ds_read2_b32 v[108:109], v19 offset0:8 offset1:41
	ds_read2_b32 v[110:111], v19 offset0:74 offset1:107
	ds_read2_b32 v[112:113], v19 offset0:140 offset1:173
	ds_read2_b32 v[114:115], v19 offset0:206 offset1:239
	ds_read2_b32 v[116:117], v19 offset0:16 offset1:49
	ds_read2_b32 v[118:119], v19 offset0:82 offset1:115
	ds_read2_b32 v[120:121], v19 offset0:148 offset1:181
	ds_read2_b32 v[122:123], v19 offset0:214 offset1:247
	ds_read2_b32 v[124:125], v19 offset0:24 offset1:57
	ds_read2_b32 v[126:127], v19 offset0:90 offset1:123
	ds_read2_b32 v[128:129], v19 offset0:156 offset1:189
	ds_read2_b32 v[130:131], v19 offset0:222 offset1:255
	s_waitcnt lgkmcnt(0)
	s_and_b32 s4, s4, 0x7e0
	v_or_b32_e32 v4, s4, v3
	s_waitcnt lgkmcnt(0)
	v_cvt_pk_bf16_f32 v26, v100, v101
	s_addk_i32 s0, 0xb400
	v_mul_u32_u24_e32 v4, 0x1600, v4
	s_waitcnt lgkmcnt(0)
	v_cvt_pk_bf16_f32 v27, v102, v103
	v_lshl_add_u64 v[32:33], s[0:1], 1, v[6:7]
	v_lshlrev_b32_e32 v4, 1, v4
	s_waitcnt lgkmcnt(0)
	v_cvt_pk_bf16_f32 v28, v104, v105
	s_waitcnt lgkmcnt(0)
	v_cvt_pk_bf16_f32 v29, v106, v107
	v_lshl_add_u64 v[34:35], v[32:33], 0, v[4:5]
	v_or_b32_e32 v4, s4, v49
	global_store_dwordx4 v[34:35], v[26:29], off
	s_nop 1
	v_mul_u32_u24_e32 v4, 0x1600, v4
	v_lshlrev_b32_e32 v4, 1, v4
	s_waitcnt lgkmcnt(0)
	v_cvt_pk_bf16_f32 v26, v108, v109
	s_waitcnt lgkmcnt(0)
	v_cvt_pk_bf16_f32 v27, v110, v111
	s_waitcnt lgkmcnt(0)
	v_cvt_pk_bf16_f32 v28, v112, v113
	s_waitcnt lgkmcnt(0)
	v_cvt_pk_bf16_f32 v29, v114, v115
	v_lshl_add_u64 v[34:35], v[32:33], 0, v[4:5]
	v_or_b32_e32 v4, s4, v50
	global_store_dwordx4 v[34:35], v[26:29], off
	s_nop 1
	v_mul_u32_u24_e32 v4, 0x1600, v4
	v_lshlrev_b32_e32 v4, 1, v4
	s_waitcnt lgkmcnt(0)
	v_cvt_pk_bf16_f32 v26, v116, v117
	s_waitcnt lgkmcnt(0)
	v_cvt_pk_bf16_f32 v27, v118, v119
	s_waitcnt lgkmcnt(0)
	v_cvt_pk_bf16_f32 v28, v120, v121
	s_waitcnt lgkmcnt(0)
	v_cvt_pk_bf16_f32 v29, v122, v123
	v_lshl_add_u64 v[34:35], v[32:33], 0, v[4:5]
	global_store_dwordx4 v[34:35], v[26:29], off
	s_nop 1
	v_or_b32_e32 v4, s4, v51
	v_mul_u32_u24_e32 v4, 0x1600, v4
	s_waitcnt lgkmcnt(0)
	v_cvt_pk_bf16_f32 v26, v124, v125
	s_waitcnt lgkmcnt(0)
	v_cvt_pk_bf16_f32 v27, v126, v127
	s_waitcnt lgkmcnt(0)
	v_cvt_pk_bf16_f32 v28, v128, v129
	v_lshlrev_b32_e32 v4, 1, v4
	s_waitcnt lgkmcnt(0)
	v_cvt_pk_bf16_f32 v29, v130, v131
	v_lshl_add_u64 v[30:31], v[32:33], 0, v[4:5]
	global_store_dwordx4 v[30:31], v[26:29], off
	s_nop 1
	s_waitcnt lgkmcnt(0)
	s_mov_b64 s[4:5], 0

; #define LAS __attribute__((address_space(3)))
; __device__ __forceinline__ unsigned cvt_pk_bf16(float lo, float hi) { unsigned r; asm volatile("v_cvt_pk_bf16_f32 %0, %1, %2" : "=v"(r) : "v"(lo), "v"(hi)); return r; }
;     ...
;     const int c = lane & 7;
; #pragma unroll
;     for (int j = 0; j < 4; ++j) { const int n = (lane >> 3) + 8 * j; const LAS float* s = scr + (8 * c) * 33 + n;
;         u32x4 o; o.x = cvt_pk_bf16(s[0 * 33], s[1 * 33]); o.y = cvt_pk_bf16(s[2 * 33], s[3 * 33]); o.z = cvt_pk_bf16(s[4 * 33], s[5 * 33]); o.w = cvt_pk_bf16(s[6 * 33], s[7 * 33]);
;         const int nn = n0 + n; const int orow = mode ? ((nn >> 7) * 256 + (nn & 127) + (mode == 2 ? 128 : 0)) : nn;
;         *(u32x4*)(WT + (size_t)orow * K + k0 + 8 * c) = o; }
;     asm volatile("s_waitcnt lgkmcnt(0)" ::: "memory");
.LBB0_74:
	s_lshl_b32 s0, s19, 6
	s_waitcnt lgkmcnt(0)
	ds_read2_b32 v[100:101], v19 offset1:33
	ds_read2_b32 v[102:103], v19 offset0:66 offset1:99
	ds_read2_b32 v[104:105], v19 offset0:132 offset1:165
	ds_read2_b32 v[106:107], v19 offset0:198 offset1:231
	ds_read2_b32 v[108:109], v19 offset0:8 offset1:41
	ds_read2_b32 v[110:111], v19 offset0:74 offset1:107
	ds_read2_b32 v[112:113], v19 offset0:140 offset1:173
	ds_read2_b32 v[114:115], v19 offset0:206 offset1:239
	ds_read2_b32 v[116:117], v19 offset0:16 offset1:49
	ds_read2_b32 v[118:119], v19 offset0:82 offset1:115
	ds_read2_b32 v[120:121], v19 offset0:148 offset1:181
	ds_read2_b32 v[122:123], v19 offset0:214 offset1:247
	ds_read2_b32 v[124:125], v19 offset0:24 offset1:57
	ds_read2_b32 v[126:127], v19 offset0:90 offset1:123
	ds_read2_b32 v[128:129], v19 offset0:156 offset1:189
	ds_read2_b32 v[130:131], v19 offset0:222 offset1:255
	s_waitcnt lgkmcnt(0)
	s_and_b32 s5, s13, 0x60
	s_and_b32 s6, s0, 0x3f00
	s_and_b32 s4, 0xffff, s20
	v_or_b32_e32 v4, s5, v3
	s_bitset1_b32 s6, 7
	s_waitcnt lgkmcnt(0)
	v_cvt_pk_bf16_f32 v26, v100, v101
	s_lshl_b32 s0, s4, 1
	v_or_b32_e32 v4, s6, v4
	s_waitcnt lgkmcnt(0)
	v_cvt_pk_bf16_f32 v27, v102, v103
	v_lshl_add_u64 v[32:33], v[8:9], 0, s[0:1]
	v_lshlrev_b32_e32 v4, 12, v4
	s_waitcnt lgkmcnt(0)
	v_cvt_pk_bf16_f32 v28, v104, v105
	s_waitcnt lgkmcnt(0)
	v_cvt_pk_bf16_f32 v29, v106, v107
	v_lshl_add_u64 v[34:35], v[32:33], 0, v[4:5]
	v_or_b32_e32 v4, s5, v49
	global_store_dwordx4 v[34:35], v[26:29], off
	s_nop 1
	v_or_b32_e32 v4, s6, v4
	v_lshlrev_b32_e32 v4, 12, v4
	s_waitcnt lgkmcnt(0)
	v_cvt_pk_bf16_f32 v26, v108, v109
	s_waitcnt lgkmcnt(0)
	v_cvt_pk_bf16_f32 v27, v110, v111
	s_waitcnt lgkmcnt(0)
	v_cvt_pk_bf16_f32 v28, v112, v113
	s_waitcnt lgkmcnt(0)
	v_cvt_pk_bf16_f32 v29, v114, v115
	v_lshl_add_u64 v[34:35], v[32:33], 0, v[4:5]
	v_or_b32_e32 v4, s5, v50
	global_store_dwordx4 v[34:35], v[26:29], off
	s_nop 1
	v_or_b32_e32 v4, s6, v4
	v_lshlrev_b32_e32 v4, 12, v4
	s_waitcnt lgkmcnt(0)
	v_cvt_pk_bf16_f32 v26, v116, v117
	s_waitcnt lgkmcnt(0)
	v_cvt_pk_bf16_f32 v27, v118, v119
	s_waitcnt lgkmcnt(0)
	v_cvt_pk_bf16_f32 v28, v120, v121
	s_waitcnt lgkmcnt(0)
	v_cvt_pk_bf16_f32 v29, v122, v123
	v_lshl_add_u64 v[34:35], v[32:33], 0, v[4:5]
	global_store_dwordx4 v[34:35], v[26:29], off
	s_nop 1
	v_or_b32_e32 v4, s5, v51
	v_or_b32_e32 v4, s6, v4
	s_waitcnt lgkmcnt(0)
	v_cvt_pk_bf16_f32 v26, v124, v125
	s_waitcnt lgkmcnt(0)
	v_cvt_pk_bf16_f32 v27, v126, v127
	s_waitcnt lgkmcnt(0)
	v_cvt_pk_bf16_f32 v28, v128, v129
	v_lshlrev_b32_e32 v4, 12, v4
	s_waitcnt lgkmcnt(0)
	v_cvt_pk_bf16_f32 v29, v130, v131
	v_lshl_add_u64 v[30:31], v[32:33], 0, v[4:5]
	global_store_dwordx4 v[30:31], v[26:29], off
	s_nop 1
	s_waitcnt lgkmcnt(0)

; #define LAS __attribute__((address_space(3)))
; __device__ __forceinline__ unsigned cvt_pk_bf16(float lo, float hi) { unsigned r; asm volatile("v_cvt_pk_bf16_f32 %0, %1, %2" : "=v"(r) : "v"(lo), "v"(hi)); return r; }
;     ...
;     const int c = lane & 7;
; #pragma unroll
;     for (int j = 0; j < 4; ++j) { const int n = (lane >> 3) + 8 * j; const LAS float* s = scr + (8 * c) * 33 + n;
;         u32x4 o; o.x = cvt_pk_bf16(s[0 * 33], s[1 * 33]); o.y = cvt_pk_bf16(s[2 * 33], s[3 * 33]); o.z = cvt_pk_bf16(s[4 * 33], s[5 * 33]); o.w = cvt_pk_bf16(s[6 * 33], s[7 * 33]);
;         const int nn = n0 + n; const int orow = mode ? ((nn >> 7) * 256 + (nn & 127) + (mode == 2 ? 128 : 0)) : nn;
;         *(u32x4*)(WT + (size_t)orow * K + k0 + 8 * c) = o; }
;     asm volatile("s_waitcnt lgkmcnt(0)" ::: "memory");
.LBB0_95:
	s_waitcnt lgkmcnt(0)
	ds_read2_b32 v[100:101], v19 offset1:33
	ds_read2_b32 v[102:103], v19 offset0:66 offset1:99
	ds_read2_b32 v[104:105], v19 offset0:132 offset1:165
	ds_read2_b32 v[106:107], v19 offset0:198 offset1:231
	ds_read2_b32 v[108:109], v19 offset0:8 offset1:41
	ds_read2_b32 v[110:111], v19 offset0:74 offset1:107
	ds_read2_b32 v[112:113], v19 offset0:140 offset1:173
	ds_read2_b32 v[114:115], v19 offset0:206 offset1:239
	ds_read2_b32 v[116:117], v19 offset0:16 offset1:49
	ds_read2_b32 v[118:119], v19 offset0:82 offset1:115
	ds_read2_b32 v[120:121], v19 offset0:148 offset1:181
	ds_read2_b32 v[122:123], v19 offset0:214 offset1:247
	ds_read2_b32 v[124:125], v19 offset0:24 offset1:57
	ds_read2_b32 v[126:127], v19 offset0:90 offset1:123
	ds_read2_b32 v[128:129], v19 offset0:156 offset1:189
	ds_read2_b32 v[130:131], v19 offset0:222 offset1:255
	s_waitcnt lgkmcnt(0)
	s_lshl_b32 s0, s19, 6
	s_and_b32 s5, s13, 0x60
	s_and_b32 s4, 0xffff, s20
	s_and_b32 s6, s0, 0x3f00
	v_or_b32_e32 v4, s5, v3
	s_waitcnt lgkmcnt(0)
	v_cvt_pk_bf16_f32 v26, v100, v101
	s_lshl_b32 s0, s4, 1
	v_or_b32_e32 v4, s6, v4
	s_waitcnt lgkmcnt(0)
	v_cvt_pk_bf16_f32 v27, v102, v103
	v_lshl_add_u64 v[32:33], v[8:9], 0, s[0:1]
	v_lshlrev_b32_e32 v4, 12, v4
	s_waitcnt lgkmcnt(0)
	v_cvt_pk_bf16_f32 v28, v104, v105
	s_waitcnt lgkmcnt(0)
	v_cvt_pk_bf16_f32 v29, v106, v107
	v_lshl_add_u64 v[34:35], v[32:33], 0, v[4:5]
	v_or_b32_e32 v4, s5, v49
	global_store_dwordx4 v[34:35], v[26:29], off
	s_nop 1
	v_or_b32_e32 v4, s6, v4
	v_lshlrev_b32_e32 v4, 12, v4
	s_waitcnt lgkmcnt(0)
	v_cvt_pk_bf16_f32 v26, v108, v109
	s_waitcnt lgkmcnt(0)
	v_cvt_pk_bf16_f32 v27, v110, v111
	s_waitcnt lgkmcnt(0)
	v_cvt_pk_bf16_f32 v28, v112, v113
	s_waitcnt lgkmcnt(0)
	v_cvt_pk_bf16_f32 v29, v114, v115
	v_lshl_add_u64 v[34:35], v[32:33], 0, v[4:5]
	v_or_b32_e32 v4, s5, v50
	global_store_dwordx4 v[34:35], v[26:29], off
	s_nop 1
	v_or_b32_e32 v4, s6, v4
	v_lshlrev_b32_e32 v4, 12, v4
	s_waitcnt lgkmcnt(0)
	v_cvt_pk_bf16_f32 v26, v116, v117
	s_waitcnt lgkmcnt(0)
	v_cvt_pk_bf16_f32 v27, v118, v119
	s_waitcnt lgkmcnt(0)
	v_cvt_pk_bf16_f32 v28, v120, v121
	s_waitcnt lgkmcnt(0)
	v_cvt_pk_bf16_f32 v29, v122, v123
	v_lshl_add_u64 v[34:35], v[32:33], 0, v[4:5]
	global_store_dwordx4 v[34:35], v[26:29], off
	s_nop 1
	v_or_b32_e32 v4, s5, v51
	v_or_b32_e32 v4, s6, v4
	s_waitcnt lgkmcnt(0)
	v_cvt_pk_bf16_f32 v26, v124, v125
	s_waitcnt lgkmcnt(0)
	v_cvt_pk_bf16_f32 v27, v126, v127
	s_waitcnt lgkmcnt(0)
	v_cvt_pk_bf16_f32 v28, v128, v129
	v_lshlrev_b32_e32 v4, 12, v4
	s_waitcnt lgkmcnt(0)
	v_cvt_pk_bf16_f32 v29, v130, v131
	v_lshl_add_u64 v[30:31], v[32:33], 0, v[4:5]
	global_store_dwordx4 v[30:31], v[26:29], off
	s_nop 1
	s_waitcnt lgkmcnt(0)

; #define LAS __attribute__((address_space(3)))
; __device__ __forceinline__ unsigned cvt_pk_bf16(float lo, float hi) { unsigned r; asm volatile("v_cvt_pk_bf16_f32 %0, %1, %2" : "=v"(r) : "v"(lo), "v"(hi)); return r; }
;     ...
;     for (int i = 0; i < 32; ++i) { const int kk = 2 * i + (lane >> 5); float v = __builtin_nontemporal_load(W + (size_t)(k0 + kk) * N + n0 + (lane & 31)); if (gain) v *= gain[k0 + kk]; scr[kk * 33 + (lane & 31)] = v; }
;     asm volatile("s_waitcnt lgkmcnt(0)" ::: "memory");
;     const int c = lane & 7;
; #pragma unroll
;     for (int j = 0; j < 4; ++j) { const int n = (lane >> 3) + 8 * j; const LAS float* s = scr + (8 * c) * 33 + n;
;         u32x4 o; o.x = cvt_pk_bf16(s[0 * 33], s[1 * 33]); o.y = cvt_pk_bf16(s[2 * 33], s[3 * 33]); o.z = cvt_pk_bf16(s[4 * 33], s[5 * 33]); o.w = cvt_pk_bf16(s[6 * 33], s[7 * 33]);
;         const int nn = n0 + n; const int orow = mode ? ((nn >> 7) * 256 + (nn & 127) + (mode == 2 ? 128 : 0)) : nn;
;         *(u32x4*)(WT + (size_t)orow * K + k0 + 8 * c) = o; }
;     asm volatile("s_waitcnt lgkmcnt(0)" ::: "memory");
.LBB0_99:
	v_lshl_add_u64 v[164:165], v[40:41], 0, s[4:5]
	global_load_dword v100, v[164:165], off nt
	v_lshl_add_u64 v[164:165], v[38:39], 0, s[4:5]
	global_load_dword v101, v[164:165], off nt
	v_lshl_add_u64 v[164:165], v[36:37], 0, s[4:5]
	global_load_dword v102, v[164:165], off nt
	v_lshl_add_u64 v[164:165], v[34:35], 0, s[4:5]
	global_load_dword v103, v[164:165], off nt
	v_lshl_add_u64 v[164:165], v[32:33], 0, s[4:5]
	global_load_dword v104, v[164:165], off nt
	v_lshl_add_u64 v[164:165], v[30:31], 0, s[4:5]
	global_load_dword v105, v[164:165], off nt
	v_lshl_add_u64 v[164:165], v[28:29], 0, s[4:5]
	global_load_dword v106, v[164:165], off nt
	v_lshl_add_u64 v[164:165], v[26:27], 0, s[4:5]
	global_load_dword v107, v[164:165], off nt
	s_add_u32 s4, s4, 0x20000
	s_addc_u32 s5, s5, 0
	v_lshl_add_u64 v[164:165], v[40:41], 0, s[4:5]
	global_load_dword v108, v[164:165], off nt
	v_lshl_add_u64 v[164:165], v[38:39], 0, s[4:5]
	global_load_dword v109, v[164:165], off nt
	v_lshl_add_u64 v[164:165], v[36:37], 0, s[4:5]
	global_load_dword v110, v[164:165], off nt
	v_lshl_add_u64 v[164:165], v[34:35], 0, s[4:5]
	global_load_dword v111, v[164:165], off nt
	v_lshl_add_u64 v[164:165], v[32:33], 0, s[4:5]
	global_load_dword v112, v[164:165], off nt
	v_lshl_add_u64 v[164:165], v[30:31], 0, s[4:5]
	global_load_dword v113, v[164:165], off nt
	v_lshl_add_u64 v[164:165], v[28:29], 0, s[4:5]
	global_load_dword v114, v[164:165], off nt
	v_lshl_add_u64 v[164:165], v[26:27], 0, s[4:5]
	global_load_dword v115, v[164:165], off nt
	s_add_u32 s4, s4, 0x20000
	s_addc_u32 s5, s5, 0
	v_lshl_add_u64 v[164:165], v[40:41], 0, s[4:5]
	global_load_dword v116, v[164:165], off nt
	v_lshl_add_u64 v[164:165], v[38:39], 0, s[4:5]
	global_load_dword v117, v[164:165], off nt
	v_lshl_add_u64 v[164:165], v[36:37], 0, s[4:5]
	global_load_dword v118, v[164:165], off nt
	v_lshl_add_u64 v[164:165], v[34:35], 0, s[4:5]
	global_load_dword v119, v[164:165], off nt
	v_lshl_add_u64 v[164:165], v[32:33], 0, s[4:5]
	global_load_dword v120, v[164:165], off nt
	v_lshl_add_u64 v[164:165], v[30:31], 0, s[4:5]
	global_load_dword v121, v[164:165], off nt
	v_lshl_add_u64 v[164:165], v[28:29], 0, s[4:5]
	global_load_dword v122, v[164:165], off nt
	v_lshl_add_u64 v[164:165], v[26:27], 0, s[4:5]
	global_load_dword v123, v[164:165], off nt
	s_add_u32 s4, s4, 0x20000
	s_addc_u32 s5, s5, 0
	v_lshl_add_u64 v[164:165], v[40:41], 0, s[4:5]
	global_load_dword v124, v[164:165], off nt
	v_lshl_add_u64 v[164:165], v[38:39], 0, s[4:5]
	global_load_dword v125, v[164:165], off nt
	v_lshl_add_u64 v[164:165], v[36:37], 0, s[4:5]
	global_load_dword v126, v[164:165], off nt
	v_lshl_add_u64 v[164:165], v[34:35], 0, s[4:5]
	global_load_dword v127, v[164:165], off nt
	v_lshl_add_u64 v[164:165], v[32:33], 0, s[4:5]
	global_load_dword v128, v[164:165], off nt
	v_lshl_add_u64 v[164:165], v[30:31], 0, s[4:5]
	global_load_dword v129, v[164:165], off nt
	v_lshl_add_u64 v[164:165], v[28:29], 0, s[4:5]
	global_load_dword v130, v[164:165], off nt
	v_lshl_add_u64 v[164:165], v[26:27], 0, s[4:5]
	global_load_dword v131, v[164:165], off nt
	s_add_u32 s4, s4, 0x20000
	s_addc_u32 s5, s5, 0
	s_waitcnt vmcnt(24)
	ds_write_b32 v4, v100
	ds_write_b32 v4, v101 offset:264
	ds_write_b32 v4, v102 offset:528
	ds_write_b32 v4, v103 offset:792
	ds_write_b32 v4, v104 offset:1056
	ds_write_b32 v4, v105 offset:1320
	ds_write_b32 v4, v106 offset:1584
	ds_write_b32 v4, v107 offset:1848
	s_waitcnt vmcnt(16)
	ds_write_b32 v4, v108 offset:2112
	ds_write_b32 v4, v109 offset:2376
	ds_write_b32 v4, v110 offset:2640
	ds_write_b32 v4, v111 offset:2904
	ds_write_b32 v4, v112 offset:3168
	ds_write_b32 v4, v113 offset:3432
	ds_write_b32 v4, v114 offset:3696
	ds_write_b32 v4, v115 offset:3960
	s_waitcnt vmcnt(8)
	ds_write_b32 v4, v116 offset:4224
	ds_write_b32 v4, v117 offset:4488
	ds_write_b32 v4, v118 offset:4752
	ds_write_b32 v4, v119 offset:5016
	ds_write_b32 v4, v120 offset:5280
	ds_write_b32 v4, v121 offset:5544
	ds_write_b32 v4, v122 offset:5808
	ds_write_b32 v4, v123 offset:6072
	s_waitcnt vmcnt(0)
	ds_write_b32 v4, v124 offset:6336
	ds_write_b32 v4, v125 offset:6600
	ds_write_b32 v4, v126 offset:6864
	ds_write_b32 v4, v127 offset:7128
	ds_write_b32 v4, v128 offset:7392
	ds_write_b32 v4, v129 offset:7656
	ds_write_b32 v4, v130 offset:7920
	ds_write_b32 v4, v131 offset:8184
	v_add_u32_e32 v4, 0x2100, v4
	s_waitcnt lgkmcnt(0)
	ds_read2_b32 v[100:101], v19 offset1:33
	ds_read2_b32 v[102:103], v19 offset0:66 offset1:99
	ds_read2_b32 v[104:105], v19 offset0:132 offset1:165
	ds_read2_b32 v[106:107], v19 offset0:198 offset1:231
	ds_read2_b32 v[108:109], v19 offset0:8 offset1:41
	ds_read2_b32 v[110:111], v19 offset0:74 offset1:107
	ds_read2_b32 v[112:113], v19 offset0:140 offset1:173
	ds_read2_b32 v[114:115], v19 offset0:206 offset1:239
	ds_read2_b32 v[116:117], v19 offset0:16 offset1:49
	ds_read2_b32 v[118:119], v19 offset0:82 offset1:115
	ds_read2_b32 v[120:121], v19 offset0:148 offset1:181
	ds_read2_b32 v[122:123], v19 offset0:214 offset1:247
	ds_read2_b32 v[124:125], v19 offset0:24 offset1:57
	ds_read2_b32 v[126:127], v19 offset0:90 offset1:123
	ds_read2_b32 v[128:129], v19 offset0:156 offset1:189
	ds_read2_b32 v[130:131], v19 offset0:222 offset1:255
	s_waitcnt lgkmcnt(0)
	s_add_i32 s0, s3, 0xe800
	s_lshl_b32 s4, s3, 5
	s_and_b32 s0, s0, 0xffc0
	s_and_b32 s4, s4, 0x7e0
	s_waitcnt lgkmcnt(0)
	v_cvt_pk_bf16_f32 v26, v100, v101
	s_lshl_b32 s0, s0, 1
	v_or_b32_e32 v4, s4, v3
	s_waitcnt lgkmcnt(0)
	v_cvt_pk_bf16_f32 v27, v102, v103
	v_lshl_add_u64 v[32:33], v[10:11], 0, s[0:1]
	v_lshlrev_b32_e32 v4, 12, v4
	s_waitcnt lgkmcnt(0)
	v_cvt_pk_bf16_f32 v28, v104, v105
	s_waitcnt lgkmcnt(0)
	v_cvt_pk_bf16_f32 v29, v106, v107
	v_lshl_add_u64 v[34:35], v[32:33], 0, v[4:5]
	global_store_dwordx4 v[34:35], v[26:29], off
	s_nop 1
	v_or_b32_e32 v4, s4, v49
	v_lshlrev_b32_e32 v4, 12, v4
	s_waitcnt lgkmcnt(0)
	v_cvt_pk_bf16_f32 v26, v108, v109
	s_waitcnt lgkmcnt(0)
	v_cvt_pk_bf16_f32 v27, v110, v111
	s_waitcnt lgkmcnt(0)
	v_cvt_pk_bf16_f32 v28, v112, v113
	s_waitcnt lgkmcnt(0)
	v_cvt_pk_bf16_f32 v29, v114, v115
	v_lshl_add_u64 v[34:35], v[32:33], 0, v[4:5]
	global_store_dwordx4 v[34:35], v[26:29], off
	s_nop 1
	v_or_b32_e32 v4, s4, v50
	v_lshlrev_b32_e32 v4, 12, v4
	s_waitcnt lgkmcnt(0)
	v_cvt_pk_bf16_f32 v26, v116, v117
	s_waitcnt lgkmcnt(0)
	v_cvt_pk_bf16_f32 v27, v118, v119
	s_waitcnt lgkmcnt(0)
	v_cvt_pk_bf16_f32 v28, v120, v121
	s_waitcnt lgkmcnt(0)
	v_cvt_pk_bf16_f32 v29, v122, v123
	v_lshl_add_u64 v[34:35], v[32:33], 0, v[4:5]
	global_store_dwordx4 v[34:35], v[26:29], off
	s_nop 1
	v_or_b32_e32 v4, s4, v51
	v_lshlrev_b32_e32 v4, 12, v4
	s_waitcnt lgkmcnt(0)
	v_cvt_pk_bf16_f32 v26, v124, v125
	s_waitcnt lgkmcnt(0)
	v_cvt_pk_bf16_f32 v27, v126, v127
	s_waitcnt lgkmcnt(0)
	v_cvt_pk_bf16_f32 v28, v128, v129
	s_waitcnt lgkmcnt(0)
	v_cvt_pk_bf16_f32 v29, v130, v131
	v_lshl_add_u64 v[30:31], v[32:33], 0, v[4:5]
	global_store_dwordx4 v[30:31], v[26:29], off
	s_nop 1
	s_waitcnt lgkmcnt(0)

; #define LAS __attribute__((address_space(3)))
; __device__ __forceinline__ unsigned cvt_pk_bf16(float lo, float hi) { unsigned r; asm volatile("v_cvt_pk_bf16_f32 %0, %1, %2" : "=v"(r) : "v"(lo), "v"(hi)); return r; }
;     ...
;     const int c = lane & 7;
; #pragma unroll
;     for (int j = 0; j < 4; ++j) { const int n = (lane >> 3) + 8 * j; const LAS float* s = scr + (8 * c) * 33 + n;
;         u32x4 o; o.x = cvt_pk_bf16(s[0 * 33], s[1 * 33]); o.y = cvt_pk_bf16(s[2 * 33], s[3 * 33]); o.z = cvt_pk_bf16(s[4 * 33], s[5 * 33]); o.w = cvt_pk_bf16(s[6 * 33], s[7 * 33]);
;         const int nn = n0 + n; const int orow = mode ? ((nn >> 7) * 256 + (nn & 127) + (mode == 2 ? 128 : 0)) : nn;
;         *(u32x4*)(WT + (size_t)orow * K + k0 + 8 * c) = o; }
;     asm volatile("s_waitcnt lgkmcnt(0)" ::: "memory");
.LBB0_158:
	s_waitcnt lgkmcnt(0)
	ds_read2_b32 v[100:101], v40 offset1:33
	ds_read2_b32 v[102:103], v40 offset0:66 offset1:99
	ds_read2_b32 v[104:105], v40 offset0:132 offset1:165
	ds_read2_b32 v[106:107], v40 offset0:198 offset1:231
	ds_read2_b32 v[108:109], v40 offset0:8 offset1:41
	ds_read2_b32 v[110:111], v40 offset0:74 offset1:107
	ds_read2_b32 v[112:113], v40 offset0:140 offset1:173
	ds_read2_b32 v[114:115], v40 offset0:206 offset1:239
	ds_read2_b32 v[116:117], v40 offset0:16 offset1:49
	ds_read2_b32 v[118:119], v40 offset0:82 offset1:115
	ds_read2_b32 v[120:121], v40 offset0:148 offset1:181
	ds_read2_b32 v[122:123], v40 offset0:214 offset1:247
	ds_read2_b32 v[124:125], v40 offset0:24 offset1:57
	ds_read2_b32 v[126:127], v40 offset0:90 offset1:123
	ds_read2_b32 v[128:129], v40 offset0:156 offset1:189
	ds_read2_b32 v[130:131], v40 offset0:222 offset1:255
	s_waitcnt lgkmcnt(0)
	s_waitcnt lgkmcnt(0)
	v_cvt_pk_bf16_f32 v18, v100, v101
	s_waitcnt lgkmcnt(0)
	v_cvt_pk_bf16_f32 v19, v102, v103
	s_waitcnt lgkmcnt(0)
	v_cvt_pk_bf16_f32 v20, v104, v105
	s_waitcnt lgkmcnt(0)
	v_cvt_pk_bf16_f32 v21, v106, v107
	v_or_b32_e32 v24, s14, v13
	v_ashrrev_i32_e32 v25, 31, v24
	v_lshl_add_u64 v[22:23], s[16:17], 1, v[8:9]
	v_lshlrev_b64 v[24:25], 12, v[24:25]
	v_lshl_add_u64 v[24:25], v[22:23], 0, v[24:25]
	global_store_dwordx4 v[24:25], v[18:21], off
	s_nop 1
	s_waitcnt lgkmcnt(0)
	v_cvt_pk_bf16_f32 v18, v108, v109
	s_waitcnt lgkmcnt(0)
	v_cvt_pk_bf16_f32 v19, v110, v111
	s_waitcnt lgkmcnt(0)
	v_cvt_pk_bf16_f32 v20, v112, v113
	s_waitcnt lgkmcnt(0)
	v_cvt_pk_bf16_f32 v21, v114, v115
	v_or_b32_e32 v24, s14, v41
	v_ashrrev_i32_e32 v25, 31, v24
	v_lshlrev_b64 v[24:25], 12, v[24:25]
	v_lshl_add_u64 v[24:25], v[22:23], 0, v[24:25]
	global_store_dwordx4 v[24:25], v[18:21], off
	s_nop 1
	s_waitcnt lgkmcnt(0)
	v_cvt_pk_bf16_f32 v18, v116, v117
	s_waitcnt lgkmcnt(0)
	v_cvt_pk_bf16_f32 v19, v118, v119
	s_waitcnt lgkmcnt(0)
	v_cvt_pk_bf16_f32 v20, v120, v121
	s_waitcnt lgkmcnt(0)
	v_cvt_pk_bf16_f32 v21, v122, v123
	v_or_b32_e32 v24, s14, v42
	v_ashrrev_i32_e32 v25, 31, v24
	v_lshlrev_b64 v[24:25], 12, v[24:25]
	v_lshl_add_u64 v[24:25], v[22:23], 0, v[24:25]
	global_store_dwordx4 v[24:25], v[18:21], off
	s_nop 1
	s_waitcnt lgkmcnt(0)
	v_cvt_pk_bf16_f32 v18, v124, v125
	s_waitcnt lgkmcnt(0)
	v_cvt_pk_bf16_f32 v19, v126, v127
	s_waitcnt lgkmcnt(0)
	v_cvt_pk_bf16_f32 v20, v128, v129
	s_waitcnt lgkmcnt(0)
	v_cvt_pk_bf16_f32 v21, v130, v131
	v_or_b32_e32 v24, s14, v43
	v_ashrrev_i32_e32 v25, 31, v24
	v_lshlrev_b64 v[24:25], 12, v[24:25]
	v_lshl_add_u64 v[22:23], v[22:23], 0, v[24:25]
	global_store_dwordx4 v[22:23], v[18:21], off
	s_nop 1
	s_waitcnt lgkmcnt(0)

; #define LAS __attribute__((address_space(3)))
; __device__ __forceinline__ unsigned cvt_pk_bf16(float lo, float hi) { unsigned r; asm volatile("v_cvt_pk_bf16_f32 %0, %1, %2" : "=v"(r) : "v"(lo), "v"(hi)); return r; }
;     ...
;     const int c = lane & 7;
; #pragma unroll
;     for (int j = 0; j < 4; ++j) { const int n = (lane >> 3) + 8 * j; const LAS float* s = scr + (8 * c) * 33 + n;
;         u32x4 o; o.x = cvt_pk_bf16(s[0 * 33], s[1 * 33]); o.y = cvt_pk_bf16(s[2 * 33], s[3 * 33]); o.z = cvt_pk_bf16(s[4 * 33], s[5 * 33]); o.w = cvt_pk_bf16(s[6 * 33], s[7 * 33]);
;         const int nn = n0 + n; const int orow = mode ? ((nn >> 7) * 256 + (nn & 127) + (mode == 2 ? 128 : 0)) : nn;
;         *(u32x4*)(WT + (size_t)orow * K + k0 + 8 * c) = o; }
;     asm volatile("s_waitcnt lgkmcnt(0)" ::: "memory");
.LBB0_180:
	s_waitcnt lgkmcnt(0)
	ds_read2_b32 v[100:101], v40 offset1:33
	ds_read2_b32 v[102:103], v40 offset0:66 offset1:99
	ds_read2_b32 v[104:105], v40 offset0:132 offset1:165
	ds_read2_b32 v[106:107], v40 offset0:198 offset1:231
	ds_read2_b32 v[108:109], v40 offset0:8 offset1:41
	ds_read2_b32 v[110:111], v40 offset0:74 offset1:107
	ds_read2_b32 v[112:113], v40 offset0:140 offset1:173
	ds_read2_b32 v[114:115], v40 offset0:206 offset1:239
	ds_read2_b32 v[116:117], v40 offset0:16 offset1:49
	ds_read2_b32 v[118:119], v40 offset0:82 offset1:115
	ds_read2_b32 v[120:121], v40 offset0:148 offset1:181
	ds_read2_b32 v[122:123], v40 offset0:214 offset1:247
	ds_read2_b32 v[124:125], v40 offset0:24 offset1:57
	ds_read2_b32 v[126:127], v40 offset0:90 offset1:123
	ds_read2_b32 v[128:129], v40 offset0:156 offset1:189
	ds_read2_b32 v[130:131], v40 offset0:222 offset1:255
	s_waitcnt lgkmcnt(0)
	s_lshl_b32 s10, s10, 6
	s_and_b32 s3, s3, 0x60
	s_and_b32 s10, s10, 0x3f00
	s_and_b32 s11, 0xffff, s11
	s_waitcnt lgkmcnt(0)
	v_cvt_pk_bf16_f32 v20, v100, v101
	v_or_b32_e32 v0, s3, v13
	s_lshl_b32 s8, s11, 1
	s_waitcnt lgkmcnt(0)
	v_cvt_pk_bf16_f32 v21, v102, v103
	v_or_b32_e32 v0, s10, v0
	v_lshl_add_u64 v[18:19], v[4:5], 0, s[8:9]
	s_waitcnt lgkmcnt(0)
	v_cvt_pk_bf16_f32 v22, v104, v105
	v_lshlrev_b32_e32 v0, 12, v0
	s_waitcnt lgkmcnt(0)
	v_cvt_pk_bf16_f32 v23, v106, v107
	v_lshl_add_u64 v[24:25], v[18:19], 0, v[0:1]
	global_store_dwordx4 v[24:25], v[20:23], off
	s_nop 1
	v_or_b32_e32 v0, s3, v41
	s_waitcnt lgkmcnt(0)
	v_cvt_pk_bf16_f32 v20, v108, v109
	s_waitcnt lgkmcnt(0)
	v_cvt_pk_bf16_f32 v21, v110, v111
	v_or_b32_e32 v0, s10, v0
	s_waitcnt lgkmcnt(0)
	v_cvt_pk_bf16_f32 v22, v112, v113
	v_lshlrev_b32_e32 v0, 12, v0
	s_waitcnt lgkmcnt(0)
	v_cvt_pk_bf16_f32 v23, v114, v115
	v_lshl_add_u64 v[24:25], v[18:19], 0, v[0:1]
	global_store_dwordx4 v[24:25], v[20:23], off
	s_nop 1
	v_or_b32_e32 v0, s3, v42
	s_waitcnt lgkmcnt(0)
	v_cvt_pk_bf16_f32 v20, v116, v117
	s_waitcnt lgkmcnt(0)
	v_cvt_pk_bf16_f32 v21, v118, v119
	v_or_b32_e32 v0, s10, v0
	s_waitcnt lgkmcnt(0)
	v_cvt_pk_bf16_f32 v22, v120, v121
	v_lshlrev_b32_e32 v0, 12, v0
	s_waitcnt lgkmcnt(0)
	v_cvt_pk_bf16_f32 v23, v122, v123
	v_lshl_add_u64 v[24:25], v[18:19], 0, v[0:1]
	v_or_b32_e32 v0, s3, v43
	global_store_dwordx4 v[24:25], v[20:23], off
	s_nop 1
	v_or_b32_e32 v0, s10, v0
	s_waitcnt lgkmcnt(0)
	v_cvt_pk_bf16_f32 v20, v124, v125
	v_lshlrev_b32_e32 v0, 12, v0
	s_waitcnt lgkmcnt(0)
	v_cvt_pk_bf16_f32 v21, v126, v127
	v_lshl_add_u64 v[18:19], v[18:19], 0, v[0:1]
	s_waitcnt lgkmcnt(0)
	v_cvt_pk_bf16_f32 v22, v128, v129
	s_waitcnt lgkmcnt(0)
	v_cvt_pk_bf16_f32 v23, v130, v131
	global_store_dwordx4 v[18:19], v[20:23], off
	s_nop 1
	s_waitcnt lgkmcnt(0)
	s_mov_b64 s[14:15], 0

;     ...
; #pragma unroll 8
;     for (int i = 0; i < 32; ++i) { const int kk = 2 * i + (lane >> 5); float v = __builtin_nontemporal_load(W + (size_t)(k0 + kk) * N + n0 + (lane & 31)); if (gain) v *= gain[k0 + kk]; scr[kk * 33 + (lane & 31)] = v; }
;     asm volatile("s_waitcnt lgkmcnt(0)" ::: "memory");
.LBB0_183:
	v_lshl_add_u64 v[164:165], v[32:33], 0, s[14:15]
	global_load_dword v100, v[164:165], off nt
	v_lshl_add_u64 v[164:165], v[30:31], 0, s[14:15]
	global_load_dword v101, v[164:165], off nt
	v_lshl_add_u64 v[164:165], v[28:29], 0, s[14:15]
	global_load_dword v102, v[164:165], off nt
	v_lshl_add_u64 v[164:165], v[26:27], 0, s[14:15]
	global_load_dword v103, v[164:165], off nt
	v_lshl_add_u64 v[164:165], v[24:25], 0, s[14:15]
	global_load_dword v104, v[164:165], off nt
	v_lshl_add_u64 v[164:165], v[22:23], 0, s[14:15]
	global_load_dword v105, v[164:165], off nt
	v_lshl_add_u64 v[164:165], v[20:21], 0, s[14:15]
	global_load_dword v106, v[164:165], off nt
	v_lshl_add_u64 v[164:165], v[18:19], 0, s[14:15]
	global_load_dword v107, v[164:165], off nt
	s_add_u32 s14, s14, 0x20000
	s_addc_u32 s15, s15, 0
	v_lshl_add_u64 v[164:165], v[32:33], 0, s[14:15]
	global_load_dword v108, v[164:165], off nt
	v_lshl_add_u64 v[164:165], v[30:31], 0, s[14:15]
	global_load_dword v109, v[164:165], off nt
	v_lshl_add_u64 v[164:165], v[28:29], 0, s[14:15]
	global_load_dword v110, v[164:165], off nt
	v_lshl_add_u64 v[164:165], v[26:27], 0, s[14:15]
	global_load_dword v111, v[164:165], off nt
	v_lshl_add_u64 v[164:165], v[24:25], 0, s[14:15]
	global_load_dword v112, v[164:165], off nt
	v_lshl_add_u64 v[164:165], v[22:23], 0, s[14:15]
	global_load_dword v113, v[164:165], off nt
	v_lshl_add_u64 v[164:165], v[20:21], 0, s[14:15]
	global_load_dword v114, v[164:165], off nt
	v_lshl_add_u64 v[164:165], v[18:19], 0, s[14:15]
	global_load_dword v115, v[164:165], off nt
	s_add_u32 s14, s14, 0x20000
	s_addc_u32 s15, s15, 0
	v_lshl_add_u64 v[164:165], v[32:33], 0, s[14:15]
	global_load_dword v116, v[164:165], off nt
	v_lshl_add_u64 v[164:165], v[30:31], 0, s[14:15]
	global_load_dword v117, v[164:165], off nt
	v_lshl_add_u64 v[164:165], v[28:29], 0, s[14:15]
	global_load_dword v118, v[164:165], off nt
	v_lshl_add_u64 v[164:165], v[26:27], 0, s[14:15]
	global_load_dword v119, v[164:165], off nt
	v_lshl_add_u64 v[164:165], v[24:25], 0, s[14:15]
	global_load_dword v120, v[164:165], off nt
	v_lshl_add_u64 v[164:165], v[22:23], 0, s[14:15]
	global_load_dword v121, v[164:165], off nt
	v_lshl_add_u64 v[164:165], v[20:21], 0, s[14:15]
	global_load_dword v122, v[164:165], off nt
	v_lshl_add_u64 v[164:165], v[18:19], 0, s[14:15]
	global_load_dword v123, v[164:165], off nt
	s_add_u32 s14, s14, 0x20000
	s_addc_u32 s15, s15, 0
	v_lshl_add_u64 v[164:165], v[32:33], 0, s[14:15]
	global_load_dword v124, v[164:165], off nt
	v_lshl_add_u64 v[164:165], v[30:31], 0, s[14:15]
	global_load_dword v125, v[164:165], off nt
	v_lshl_add_u64 v[164:165], v[28:29], 0, s[14:15]
	global_load_dword v126, v[164:165], off nt
	v_lshl_add_u64 v[164:165], v[26:27], 0, s[14:15]
	global_load_dword v127, v[164:165], off nt
	v_lshl_add_u64 v[164:165], v[24:25], 0, s[14:15]
	global_load_dword v128, v[164:165], off nt
	v_lshl_add_u64 v[164:165], v[22:23], 0, s[14:15]
	global_load_dword v129, v[164:165], off nt
	v_lshl_add_u64 v[164:165], v[20:21], 0, s[14:15]
	global_load_dword v130, v[164:165], off nt
	v_lshl_add_u64 v[164:165], v[18:19], 0, s[14:15]
	global_load_dword v131, v[164:165], off nt
	s_add_u32 s14, s14, 0x20000
	s_addc_u32 s15, s15, 0
	s_waitcnt vmcnt(24)
	ds_write_b32 v0, v100
	ds_write_b32 v0, v101 offset:264
	ds_write_b32 v0, v102 offset:528
	ds_write_b32 v0, v103 offset:792
	ds_write_b32 v0, v104 offset:1056
	ds_write_b32 v0, v105 offset:1320
	ds_write_b32 v0, v106 offset:1584
	ds_write_b32 v0, v107 offset:1848
	s_waitcnt vmcnt(16)
; #define LAS __attribute__((address_space(3)))
; __device__ __forceinline__ unsigned cvt_pk_bf16(float lo, float hi) { unsigned r; asm volatile("v_cvt_pk_bf16_f32 %0, %1, %2" : "=v"(r) : "v"(lo), "v"(hi)); return r; }
;     ...
;     for (int i = 0; i < 32; ++i) { const int kk = 2 * i + (lane >> 5); float v = __builtin_nontemporal_load(W + (size_t)(k0 + kk) * N + n0 + (lane & 31)); if (gain) v *= gain[k0 + kk]; scr[kk * 33 + (lane & 31)] = v; }
;     asm volatile("s_waitcnt lgkmcnt(0)" ::: "memory");
;     const int c = lane & 7;
; #pragma unroll
;     for (int j = 0; j < 4; ++j) { const int n = (lane >> 3) + 8 * j; const LAS float* s = scr + (8 * c) * 33 + n;
;         u32x4 o; o.x = cvt_pk_bf16(s[0 * 33], s[1 * 33]); o.y = cvt_pk_bf16(s[2 * 33], s[3 * 33]); o.z = cvt_pk_bf16(s[4 * 33], s[5 * 33]); o.w = cvt_pk_bf16(s[6 * 33], s[7 * 33]);
;         const int nn = n0 + n; const int orow = mode ? ((nn >> 7) * 256 + (nn & 127) + (mode == 2 ? 128 : 0)) : nn;
;         *(u32x4*)(WT + (size_t)orow * K + k0 + 8 * c) = o; }
	ds_write_b32 v0, v108 offset:2112
	ds_write_b32 v0, v109 offset:2376
	ds_write_b32 v0, v110 offset:2640
	ds_write_b32 v0, v111 offset:2904
	ds_write_b32 v0, v112 offset:3168
	ds_write_b32 v0, v113 offset:3432
	ds_write_b32 v0, v114 offset:3696
	ds_write_b32 v0, v115 offset:3960
	s_waitcnt vmcnt(8)
	ds_write_b32 v0, v116 offset:4224
	ds_write_b32 v0, v117 offset:4488
	ds_write_b32 v0, v118 offset:4752
	ds_write_b32 v0, v119 offset:5016
	ds_write_b32 v0, v120 offset:5280
	ds_write_b32 v0, v121 offset:5544
	ds_write_b32 v0, v122 offset:5808
	ds_write_b32 v0, v123 offset:6072
	s_waitcnt vmcnt(0)
	ds_write_b32 v0, v124 offset:6336
	ds_write_b32 v0, v125 offset:6600
	ds_write_b32 v0, v126 offset:6864
	ds_write_b32 v0, v127 offset:7128
	ds_write_b32 v0, v128 offset:7392
	ds_write_b32 v0, v129 offset:7656
	ds_write_b32 v0, v130 offset:7920
	ds_write_b32 v0, v131 offset:8184
	v_add_u32_e32 v0, 0x2100, v0
	s_add_i32 s3, s0, 0xe800
	s_waitcnt lgkmcnt(0)
	ds_read2_b32 v[100:101], v40 offset1:33
	ds_read2_b32 v[102:103], v40 offset0:66 offset1:99
	ds_read2_b32 v[104:105], v40 offset0:132 offset1:165
	ds_read2_b32 v[106:107], v40 offset0:198 offset1:231
	ds_read2_b32 v[108:109], v40 offset0:8 offset1:41
	ds_read2_b32 v[110:111], v40 offset0:74 offset1:107
	ds_read2_b32 v[112:113], v40 offset0:140 offset1:173
	ds_read2_b32 v[114:115], v40 offset0:206 offset1:239
	ds_read2_b32 v[116:117], v40 offset0:16 offset1:49
	ds_read2_b32 v[118:119], v40 offset0:82 offset1:115
	ds_read2_b32 v[120:121], v40 offset0:148 offset1:181
	ds_read2_b32 v[122:123], v40 offset0:214 offset1:247
	ds_read2_b32 v[124:125], v40 offset0:24 offset1:57
	ds_read2_b32 v[126:127], v40 offset0:90 offset1:123
	ds_read2_b32 v[128:129], v40 offset0:156 offset1:189
	ds_read2_b32 v[130:131], v40 offset0:222 offset1:255
	s_waitcnt lgkmcnt(0)
	s_and_b32 s10, s3, 0xffc0
	s_lshl_b32 s3, s0, 5
	s_and_b32 s3, s3, 0x7e0
	s_waitcnt lgkmcnt(0)
	v_cvt_pk_bf16_f32 v18, v100, v101
	s_lshl_b32 s8, s10, 1
	s_waitcnt lgkmcnt(0)
	v_cvt_pk_bf16_f32 v19, v102, v103
	v_or_b32_e32 v0, s3, v13
	v_lshl_add_u64 v[22:23], v[6:7], 0, s[8:9]
	s_waitcnt lgkmcnt(0)
	v_cvt_pk_bf16_f32 v20, v104, v105
	v_lshlrev_b32_e32 v0, 12, v0
	s_waitcnt lgkmcnt(0)
	v_cvt_pk_bf16_f32 v21, v106, v107
	v_lshl_add_u64 v[24:25], v[22:23], 0, v[0:1]
	global_store_dwordx4 v[24:25], v[18:21], off
	s_nop 1
	v_or_b32_e32 v0, s3, v41
	s_waitcnt lgkmcnt(0)
	v_cvt_pk_bf16_f32 v18, v108, v109
	s_waitcnt lgkmcnt(0)
	v_cvt_pk_bf16_f32 v19, v110, v111
	s_waitcnt lgkmcnt(0)
	v_cvt_pk_bf16_f32 v20, v112, v113
	v_lshlrev_b32_e32 v0, 12, v0
	s_waitcnt lgkmcnt(0)
	v_cvt_pk_bf16_f32 v21, v114, v115
	v_lshl_add_u64 v[24:25], v[22:23], 0, v[0:1]
	global_store_dwordx4 v[24:25], v[18:21], off
	s_nop 1
	v_or_b32_e32 v0, s3, v42
	s_waitcnt lgkmcnt(0)
	v_cvt_pk_bf16_f32 v18, v116, v117
	s_waitcnt lgkmcnt(0)
	v_cvt_pk_bf16_f32 v19, v118, v119
	s_waitcnt lgkmcnt(0)
	v_cvt_pk_bf16_f32 v20, v120, v121
	v_lshlrev_b32_e32 v0, 12, v0
	s_waitcnt lgkmcnt(0)
	v_cvt_pk_bf16_f32 v21, v122, v123
	v_lshl_add_u64 v[24:25], v[22:23], 0, v[0:1]
	global_store_dwordx4 v[24:25], v[18:21], off
	s_nop 1
	v_or_b32_e32 v0, s3, v43
	s_waitcnt lgkmcnt(0)
	v_cvt_pk_bf16_f32 v18, v124, v125
	v_lshlrev_b32_e32 v0, 12, v0
	s_waitcnt lgkmcnt(0)
	v_cvt_pk_bf16_f32 v19, v126, v127
	v_lshl_add_u64 v[22:23], v[22:23], 0, v[0:1]
	s_waitcnt lgkmcnt(0)
	v_cvt_pk_bf16_f32 v20, v128, v129
	s_waitcnt lgkmcnt(0)
	v_cvt_pk_bf16_f32 v21, v130, v131
	global_store_dwordx4 v[22:23], v[18:21], off
	s_nop 1
	s_waitcnt lgkmcnt(0)

;     __device__ __forceinline__ void fused(f32x4 (&acc)[2][2][4][2], const Unit& u, int wr, int wc, int fr, int fq, PG8_LAS unsigned char* lds, int tid) const {
;     ...
;         asm volatile("" ::: "memory"); __builtin_amdgcn_s_barrier(); asm volatile("" ::: "memory");
;         const int qa = u.ks >> 1, qm = (u.ks & 1) * 2;
;         const f32x4* base = (const f32x4*)(partials + (size_t)slot * 4 * 65536) + tid;
; #pragma unroll
;         for (int bj = 0; bj < 2; ++bj) {
;             f32x4 pp[2][2][4];
; #pragma unroll
;             for (int mm = 0; mm < 2; ++mm)
; #pragma unroll
;                 for (int n = 0; n < 2; ++n)
; #pragma unroll
;                     for (int sl = 0; sl < 4; ++sl) pp[mm][n][sl] = base[(size_t)sl * 16384 + (size_t)(((qa * 2 + bj) * 4 + qm + mm) * 2 + n) * 512];
; #pragma unroll
;             for (int ai = 0; ai < 2; ++ai)
; #pragma unroll
;                 for (int mh = 0; mh < 2; ++mh)
;                     if (ai == qa && mh * 2 == qm) {
; #pragma unroll
;                         for (int mm = 0; mm < 2; ++mm)
; #pragma unroll
;                             for (int n = 0; n < 2; ++n) acc[ai][bj][mh * 2 + mm][n] = ((pp[mm][n][0] + pp[mm][n][1]) + pp[mm][n][2]) + pp[mm][n][3];
.LBB0_531:
	s_or_b64 exec, exec, s[14:15]
	v_readlane_b32 s2, v254, 52
	v_readlane_b32 s3, v254, 53
	s_movk_i32 s1, 0x4000
	s_barrier
	v_lshl_add_u64 v[204:205], v[130:131], 4, s[2:3]
	v_readlane_b32 s2, v255, 15
	v_readlane_b32 s3, v255, 16
	s_nop 1
	v_lshl_add_u64 v[186:187], v[204:205], 0, s[2:3]
	v_add_co_u32_e32 v134, vcc, 0x40000, v186
	v_readlane_b32 s2, v254, 56
	s_nop 0
	v_addc_co_u32_e32 v135, vcc, 0, v187, vcc
	v_add_co_u32_e32 v138, vcc, 0x80000, v186
	global_load_dwordx4 v[130:133], v[186:187], off
	s_nop 0
	global_load_dwordx4 v[134:137], v[134:135], off
	v_addc_co_u32_e32 v139, vcc, 0, v187, vcc
	v_add_co_u32_e32 v140, vcc, 0xc0000, v186
	v_readlane_b32 s3, v254, 57
	s_nop 0
	v_addc_co_u32_e32 v141, vcc, 0, v187, vcc
	v_add_co_u32_e32 v146, vcc, s68, v186
	global_load_dwordx4 v[142:145], v[138:139], off
	s_nop 0
	global_load_dwordx4 v[138:141], v[140:141], off
	v_addc_co_u32_e32 v147, vcc, 0, v187, vcc
	v_add_co_u32_e32 v150, vcc, 0x42000, v186
	s_nop 1
	v_addc_co_u32_e32 v151, vcc, 0, v187, vcc
	v_add_co_u32_e32 v154, vcc, 0x82000, v186
	global_load_dwordx4 v[146:149], v[146:147], off
	s_nop 0
	global_load_dwordx4 v[150:153], v[150:151], off
	v_addc_co_u32_e32 v155, vcc, 0, v187, vcc
	v_add_co_u32_e32 v156, vcc, 0xc2000, v186
	s_nop 1
	v_addc_co_u32_e32 v157, vcc, 0, v187, vcc
	v_add_co_u32_e32 v162, vcc, s1, v186
	s_movk_i32 s1, 0x6000
	s_nop 0
	v_addc_co_u32_e32 v163, vcc, 0, v187, vcc
	v_add_co_u32_e32 v166, vcc, 0x44000, v186
	global_load_dwordx4 v[158:161], v[154:155], off
	s_nop 0
	global_load_dwordx4 v[154:157], v[156:157], off
	v_addc_co_u32_e32 v167, vcc, 0, v187, vcc
	v_add_co_u32_e32 v170, vcc, 0x84000, v186
	global_load_dwordx4 v[162:165], v[162:163], off
	s_nop 0
	global_load_dwordx4 v[166:169], v[166:167], off
	v_addc_co_u32_e32 v171, vcc, 0, v187, vcc
	v_add_co_u32_e32 v172, vcc, 0xc4000, v186
	s_nop 1
	v_addc_co_u32_e32 v173, vcc, 0, v187, vcc
	v_add_co_u32_e32 v178, vcc, s1, v186
	global_load_dwordx4 v[174:177], v[170:171], off
	s_nop 0
	global_load_dwordx4 v[170:173], v[172:173], off
	v_addc_co_u32_e32 v179, vcc, 0, v187, vcc
	v_add_co_u32_e32 v182, vcc, 0x46000, v186
	s_nop 1
	v_addc_co_u32_e32 v183, vcc, 0, v187, vcc
	v_add_co_u32_e32 v188, vcc, 0x86000, v186
	global_load_dwordx4 v[178:181], v[178:179], off
	s_nop 0
	global_load_dwordx4 v[182:185], v[182:183], off
	v_addc_co_u32_e32 v189, vcc, 0, v187, vcc
	v_add_co_u32_e32 v186, vcc, 0xc6000, v186
	s_nop 1
	v_addc_co_u32_e32 v187, vcc, 0, v187, vcc
	global_load_dwordx4 v[190:193], v[188:189], off
	s_nop 0
	global_load_dwordx4 v[186:189], v[186:187], off
	s_waitcnt vmcnt(0)
	v_pk_add_f32 v[206:207], v[130:131], v[134:135]
	v_pk_add_f32 v[146:147], v[146:147], v[150:151]
	v_pk_add_f32 v[134:135], v[162:163], v[166:167]
	v_pk_add_f32 v[130:131], v[178:179], v[182:183]
	s_and_b64 vcc, exec, s[2:3]
	s_cbranch_vccz .LBB0_533
	v_pk_add_f32 v[42:43], v[132:133], v[136:137]
	v_pk_add_f32 v[44:45], v[206:207], v[142:143]
	v_pk_add_f32 v[42:43], v[42:43], v[144:145]
	v_pk_add_f32 v[58:59], v[44:45], v[138:139]
	v_pk_add_f32 v[60:61], v[42:43], v[140:141]
	v_pk_add_f32 v[42:43], v[148:149], v[152:153]
	v_pk_add_f32 v[44:45], v[146:147], v[158:159]
	v_pk_add_f32 v[42:43], v[42:43], v[160:161]
	v_pk_add_f32 v[46:47], v[134:135], v[174:175]
	v_pk_add_f32 v[64:65], v[42:43], v[156:157]
	v_pk_add_f32 v[42:43], v[164:165], v[168:169]
	v_pk_add_f32 v[62:63], v[44:45], v[154:155]
	v_pk_add_f32 v[42:43], v[42:43], v[176:177]
	s_waitcnt vmcnt(1)
	v_pk_add_f32 v[150:151], v[130:131], v[190:191]
	v_pk_add_f32 v[44:45], v[42:43], v[172:173]
	v_pk_add_f32 v[42:43], v[46:47], v[170:171]
	v_pk_add_f32 v[46:47], v[180:181], v[184:185]
	s_nop 0
	v_pk_add_f32 v[46:47], v[46:47], v[192:193]
	s_waitcnt vmcnt(0)
	v_pk_add_f32 v[48:49], v[46:47], v[188:189]
	v_pk_add_f32 v[46:47], v[150:151], v[186:187]

; #define LAS __attribute__((address_space(3)))
; __device__ __forceinline__ unsigned cvt_pk_bf16(float lo, float hi) { unsigned r; asm volatile("v_cvt_pk_bf16_f32 %0, %1, %2" : "=v"(r) : "v"(lo), "v"(hi)); return r; }
;     ...
;     const int c = lane & 7;
; #pragma unroll
;     for (int j = 0; j < 4; ++j) { const int n = (lane >> 3) + 8 * j; const LAS float* s = scr + (8 * c) * 33 + n;
;         u32x4 o; o.x = cvt_pk_bf16(s[0 * 33], s[1 * 33]); o.y = cvt_pk_bf16(s[2 * 33], s[3 * 33]); o.z = cvt_pk_bf16(s[4 * 33], s[5 * 33]); o.w = cvt_pk_bf16(s[6 * 33], s[7 * 33]);
;         const int nn = n0 + n; const int orow = mode ? ((nn >> 7) * 256 + (nn & 127) + (mode == 2 ? 128 : 0)) : nn;
;         *(u32x4*)(WT + (size_t)orow * K + k0 + 8 * c) = o; }
;     asm volatile("s_waitcnt lgkmcnt(0)" ::: "memory");
.LBB0_908:
	s_waitcnt lgkmcnt(0)
	ds_read2_b32 v[100:101], v44 offset1:33
	ds_read2_b32 v[102:103], v44 offset0:66 offset1:99
	ds_read2_b32 v[104:105], v44 offset0:132 offset1:165
	ds_read2_b32 v[106:107], v44 offset0:198 offset1:231
	ds_read2_b32 v[108:109], v44 offset0:8 offset1:41
	ds_read2_b32 v[110:111], v44 offset0:74 offset1:107
	ds_read2_b32 v[112:113], v44 offset0:140 offset1:173
	ds_read2_b32 v[114:115], v44 offset0:206 offset1:239
	ds_read2_b32 v[116:117], v44 offset0:16 offset1:49
	ds_read2_b32 v[118:119], v44 offset0:82 offset1:115
	ds_read2_b32 v[120:121], v44 offset0:148 offset1:181
	ds_read2_b32 v[122:123], v44 offset0:214 offset1:247
	ds_read2_b32 v[124:125], v44 offset0:24 offset1:57
	ds_read2_b32 v[126:127], v44 offset0:90 offset1:123
	ds_read2_b32 v[128:129], v44 offset0:156 offset1:189
	ds_read2_b32 v[130:131], v44 offset0:222 offset1:255
	s_waitcnt lgkmcnt(0)
	s_waitcnt lgkmcnt(0)
	v_cvt_pk_bf16_f32 v24, v100, v101
	s_waitcnt lgkmcnt(0)
	v_cvt_pk_bf16_f32 v25, v102, v103
	s_waitcnt lgkmcnt(0)
	v_cvt_pk_bf16_f32 v26, v104, v105
	s_waitcnt lgkmcnt(0)
	v_cvt_pk_bf16_f32 v27, v106, v107
	v_or_b32_e32 v30, s14, v3
	v_ashrrev_i32_e32 v31, 31, v30
	v_lshl_add_u64 v[28:29], s[16:17], 1, v[4:5]
	v_lshlrev_b64 v[30:31], 12, v[30:31]
	v_lshl_add_u64 v[30:31], v[28:29], 0, v[30:31]
	global_store_dwordx4 v[30:31], v[24:27], off
	s_nop 1
	s_waitcnt lgkmcnt(0)
	v_cvt_pk_bf16_f32 v24, v108, v109
	s_waitcnt lgkmcnt(0)
	v_cvt_pk_bf16_f32 v25, v110, v111
	s_waitcnt lgkmcnt(0)
	v_cvt_pk_bf16_f32 v26, v112, v113
	s_waitcnt lgkmcnt(0)
	v_cvt_pk_bf16_f32 v27, v114, v115
	v_or_b32_e32 v30, s14, v45
	v_ashrrev_i32_e32 v31, 31, v30
	v_lshlrev_b64 v[30:31], 12, v[30:31]
	v_lshl_add_u64 v[30:31], v[28:29], 0, v[30:31]
	global_store_dwordx4 v[30:31], v[24:27], off
	s_nop 1
	s_waitcnt lgkmcnt(0)
	v_cvt_pk_bf16_f32 v24, v116, v117
	s_waitcnt lgkmcnt(0)
	v_cvt_pk_bf16_f32 v25, v118, v119
	s_waitcnt lgkmcnt(0)
	v_cvt_pk_bf16_f32 v26, v120, v121
	s_waitcnt lgkmcnt(0)
	v_cvt_pk_bf16_f32 v27, v122, v123
	v_or_b32_e32 v30, s14, v46
	v_ashrrev_i32_e32 v31, 31, v30
	v_lshlrev_b64 v[30:31], 12, v[30:31]
	v_lshl_add_u64 v[30:31], v[28:29], 0, v[30:31]
	global_store_dwordx4 v[30:31], v[24:27], off
	s_nop 1
	s_waitcnt lgkmcnt(0)
	v_cvt_pk_bf16_f32 v24, v124, v125
	s_waitcnt lgkmcnt(0)
	v_cvt_pk_bf16_f32 v25, v126, v127
	s_waitcnt lgkmcnt(0)
	v_cvt_pk_bf16_f32 v26, v128, v129
	s_waitcnt lgkmcnt(0)
	v_cvt_pk_bf16_f32 v27, v130, v131
	v_or_b32_e32 v30, s14, v47
	v_ashrrev_i32_e32 v31, 31, v30
	v_lshlrev_b64 v[30:31], 12, v[30:31]
	v_lshl_add_u64 v[28:29], v[28:29], 0, v[30:31]
	global_store_dwordx4 v[28:29], v[24:27], off
	s_nop 1
	s_waitcnt lgkmcnt(0)

;     ...
; #pragma unroll 8
;     for (int i = 0; i < 32; ++i) { const int kk = 2 * i + (lane >> 5); float v = __builtin_nontemporal_load(W + (size_t)(k0 + kk) * N + n0 + (lane & 31)); if (gain) v *= gain[k0 + kk]; scr[kk * 33 + (lane & 31)] = v; }
;     asm volatile("s_waitcnt lgkmcnt(0)" ::: "memory");
.LBB0_915:
	v_lshl_add_u64 v[164:165], v[38:39], 0, s[14:15]
	global_load_dword v100, v[164:165], off nt
	v_lshl_add_u64 v[164:165], v[36:37], 0, s[14:15]
	global_load_dword v101, v[164:165], off nt
	v_lshl_add_u64 v[164:165], v[34:35], 0, s[14:15]
	global_load_dword v102, v[164:165], off nt
	v_lshl_add_u64 v[164:165], v[32:33], 0, s[14:15]
	global_load_dword v103, v[164:165], off nt
	v_lshl_add_u64 v[164:165], v[30:31], 0, s[14:15]
	global_load_dword v104, v[164:165], off nt
	v_lshl_add_u64 v[164:165], v[28:29], 0, s[14:15]
	global_load_dword v105, v[164:165], off nt
	v_lshl_add_u64 v[164:165], v[26:27], 0, s[14:15]
	global_load_dword v106, v[164:165], off nt
	v_lshl_add_u64 v[164:165], v[24:25], 0, s[14:15]
	global_load_dword v107, v[164:165], off nt
	s_add_u32 s14, s14, 0x20000
	s_addc_u32 s15, s15, 0
	v_lshl_add_u64 v[164:165], v[38:39], 0, s[14:15]
	global_load_dword v108, v[164:165], off nt
	v_lshl_add_u64 v[164:165], v[36:37], 0, s[14:15]
	global_load_dword v109, v[164:165], off nt
	v_lshl_add_u64 v[164:165], v[34:35], 0, s[14:15]
	global_load_dword v110, v[164:165], off nt
	v_lshl_add_u64 v[164:165], v[32:33], 0, s[14:15]
	global_load_dword v111, v[164:165], off nt
	v_lshl_add_u64 v[164:165], v[30:31], 0, s[14:15]
	global_load_dword v112, v[164:165], off nt
	v_lshl_add_u64 v[164:165], v[28:29], 0, s[14:15]
	global_load_dword v113, v[164:165], off nt
	v_lshl_add_u64 v[164:165], v[26:27], 0, s[14:15]
	global_load_dword v114, v[164:165], off nt
	v_lshl_add_u64 v[164:165], v[24:25], 0, s[14:15]
	global_load_dword v115, v[164:165], off nt
	s_add_u32 s14, s14, 0x20000
	s_addc_u32 s15, s15, 0
	v_lshl_add_u64 v[164:165], v[38:39], 0, s[14:15]
	global_load_dword v116, v[164:165], off nt
	v_lshl_add_u64 v[164:165], v[36:37], 0, s[14:15]
	global_load_dword v117, v[164:165], off nt
	v_lshl_add_u64 v[164:165], v[34:35], 0, s[14:15]
	global_load_dword v118, v[164:165], off nt
	v_lshl_add_u64 v[164:165], v[32:33], 0, s[14:15]
	global_load_dword v119, v[164:165], off nt
	v_lshl_add_u64 v[164:165], v[30:31], 0, s[14:15]
	global_load_dword v120, v[164:165], off nt
	v_lshl_add_u64 v[164:165], v[28:29], 0, s[14:15]
	global_load_dword v121, v[164:165], off nt
	v_lshl_add_u64 v[164:165], v[26:27], 0, s[14:15]
	global_load_dword v122, v[164:165], off nt
	v_lshl_add_u64 v[164:165], v[24:25], 0, s[14:15]
	global_load_dword v123, v[164:165], off nt
	s_add_u32 s14, s14, 0x20000
	s_addc_u32 s15, s15, 0
	v_lshl_add_u64 v[164:165], v[38:39], 0, s[14:15]
	global_load_dword v124, v[164:165], off nt
	v_lshl_add_u64 v[164:165], v[36:37], 0, s[14:15]
	global_load_dword v125, v[164:165], off nt
	v_lshl_add_u64 v[164:165], v[34:35], 0, s[14:15]
	global_load_dword v126, v[164:165], off nt
	v_lshl_add_u64 v[164:165], v[32:33], 0, s[14:15]
	global_load_dword v127, v[164:165], off nt
	v_lshl_add_u64 v[164:165], v[30:31], 0, s[14:15]
	global_load_dword v128, v[164:165], off nt
	v_lshl_add_u64 v[164:165], v[28:29], 0, s[14:15]
	global_load_dword v129, v[164:165], off nt
	v_lshl_add_u64 v[164:165], v[26:27], 0, s[14:15]
	global_load_dword v130, v[164:165], off nt
	v_lshl_add_u64 v[164:165], v[24:25], 0, s[14:15]
	global_load_dword v131, v[164:165], off nt
	s_add_u32 s14, s14, 0x20000
	s_addc_u32 s15, s15, 0
	s_waitcnt vmcnt(24)
	ds_write_b32 v0, v100
	ds_write_b32 v0, v101 offset:264
	ds_write_b32 v0, v102 offset:528
	ds_write_b32 v0, v103 offset:792
	ds_write_b32 v0, v104 offset:1056
	ds_write_b32 v0, v105 offset:1320
	ds_write_b32 v0, v106 offset:1584
	ds_write_b32 v0, v107 offset:1848
	s_waitcnt vmcnt(16)
; #define LAS __attribute__((address_space(3)))
; __device__ __forceinline__ unsigned cvt_pk_bf16(float lo, float hi) { unsigned r; asm volatile("v_cvt_pk_bf16_f32 %0, %1, %2" : "=v"(r) : "v"(lo), "v"(hi)); return r; }
;     ...
;     for (int i = 0; i < 32; ++i) { const int kk = 2 * i + (lane >> 5); float v = __builtin_nontemporal_load(W + (size_t)(k0 + kk) * N + n0 + (lane & 31)); if (gain) v *= gain[k0 + kk]; scr[kk * 33 + (lane & 31)] = v; }
;     asm volatile("s_waitcnt lgkmcnt(0)" ::: "memory");
;     const int c = lane & 7;
; #pragma unroll
;     for (int j = 0; j < 4; ++j) { const int n = (lane >> 3) + 8 * j; const LAS float* s = scr + (8 * c) * 33 + n;
;         u32x4 o; o.x = cvt_pk_bf16(s[0 * 33], s[1 * 33]); o.y = cvt_pk_bf16(s[2 * 33], s[3 * 33]); o.z = cvt_pk_bf16(s[4 * 33], s[5 * 33]); o.w = cvt_pk_bf16(s[6 * 33], s[7 * 33]);
;         const int nn = n0 + n; const int orow = mode ? ((nn >> 7) * 256 + (nn & 127) + (mode == 2 ? 128 : 0)) : nn;
;         *(u32x4*)(WT + (size_t)orow * K + k0 + 8 * c) = o; }
	ds_write_b32 v0, v108 offset:2112
	ds_write_b32 v0, v109 offset:2376
	ds_write_b32 v0, v110 offset:2640
	ds_write_b32 v0, v111 offset:2904
	ds_write_b32 v0, v112 offset:3168
	ds_write_b32 v0, v113 offset:3432
	ds_write_b32 v0, v114 offset:3696
	ds_write_b32 v0, v115 offset:3960
	s_waitcnt vmcnt(8)
	ds_write_b32 v0, v116 offset:4224
	ds_write_b32 v0, v117 offset:4488
	ds_write_b32 v0, v118 offset:4752
	ds_write_b32 v0, v119 offset:5016
	ds_write_b32 v0, v120 offset:5280
	ds_write_b32 v0, v121 offset:5544
	ds_write_b32 v0, v122 offset:5808
	ds_write_b32 v0, v123 offset:6072
	s_waitcnt vmcnt(0)
	ds_write_b32 v0, v124 offset:6336
	ds_write_b32 v0, v125 offset:6600
	ds_write_b32 v0, v126 offset:6864
	ds_write_b32 v0, v127 offset:7128
	ds_write_b32 v0, v128 offset:7392
	ds_write_b32 v0, v129 offset:7656
	ds_write_b32 v0, v130 offset:7920
	ds_write_b32 v0, v131 offset:8184
	v_add_u32_e32 v0, 0x2100, v0
	s_and_b32 s11, s3, 0x7fffffc0
	s_add_i32 s8, s11, 0xffffb400
	s_lshl_b32 s11, s3, 5
	s_waitcnt lgkmcnt(0)
	ds_read2_b32 v[100:101], v44 offset1:33
	ds_read2_b32 v[102:103], v44 offset0:66 offset1:99
	ds_read2_b32 v[104:105], v44 offset0:132 offset1:165
	ds_read2_b32 v[106:107], v44 offset0:198 offset1:231
	ds_read2_b32 v[108:109], v44 offset0:8 offset1:41
	ds_read2_b32 v[110:111], v44 offset0:74 offset1:107
	ds_read2_b32 v[112:113], v44 offset0:140 offset1:173
	ds_read2_b32 v[114:115], v44 offset0:206 offset1:239
	ds_read2_b32 v[116:117], v44 offset0:16 offset1:49
	ds_read2_b32 v[118:119], v44 offset0:82 offset1:115
	ds_read2_b32 v[120:121], v44 offset0:148 offset1:181
	ds_read2_b32 v[122:123], v44 offset0:214 offset1:247
	ds_read2_b32 v[124:125], v44 offset0:24 offset1:57
	ds_read2_b32 v[126:127], v44 offset0:90 offset1:123
	ds_read2_b32 v[128:129], v44 offset0:156 offset1:189
	ds_read2_b32 v[130:131], v44 offset0:222 offset1:255
	s_waitcnt lgkmcnt(0)
	s_and_b32 s11, s11, 0x7e0
	s_waitcnt lgkmcnt(0)
	v_cvt_pk_bf16_f32 v26, v100, v101
	v_or_b32_e32 v0, s11, v3
	s_waitcnt lgkmcnt(0)
	v_cvt_pk_bf16_f32 v27, v102, v103
	v_mul_u32_u24_e32 v0, 0x1600, v0
	v_lshl_add_u64 v[24:25], s[8:9], 1, v[6:7]
	s_waitcnt lgkmcnt(0)
	v_cvt_pk_bf16_f32 v28, v104, v105
	v_lshlrev_b32_e32 v0, 1, v0
	s_waitcnt lgkmcnt(0)
	v_cvt_pk_bf16_f32 v29, v106, v107
	v_lshl_add_u64 v[30:31], v[24:25], 0, v[0:1]
	global_store_dwordx4 v[30:31], v[26:29], off
	s_nop 1
	v_or_b32_e32 v0, s11, v45
	s_waitcnt lgkmcnt(0)
	v_cvt_pk_bf16_f32 v26, v108, v109
	s_waitcnt lgkmcnt(0)
	v_cvt_pk_bf16_f32 v27, v110, v111
	v_mul_u32_u24_e32 v0, 0x1600, v0
	s_waitcnt lgkmcnt(0)
	v_cvt_pk_bf16_f32 v28, v112, v113
	v_lshlrev_b32_e32 v0, 1, v0
	s_waitcnt lgkmcnt(0)
	v_cvt_pk_bf16_f32 v29, v114, v115
	v_lshl_add_u64 v[30:31], v[24:25], 0, v[0:1]
	global_store_dwordx4 v[30:31], v[26:29], off
	s_nop 1
	v_or_b32_e32 v0, s11, v46
	s_waitcnt lgkmcnt(0)
	v_cvt_pk_bf16_f32 v26, v116, v117
	s_waitcnt lgkmcnt(0)
	v_cvt_pk_bf16_f32 v27, v118, v119
	v_mul_u32_u24_e32 v0, 0x1600, v0
	s_waitcnt lgkmcnt(0)
	v_cvt_pk_bf16_f32 v28, v120, v121
	v_lshlrev_b32_e32 v0, 1, v0
	s_waitcnt lgkmcnt(0)
	v_cvt_pk_bf16_f32 v29, v122, v123
	v_lshl_add_u64 v[30:31], v[24:25], 0, v[0:1]
	v_or_b32_e32 v0, s11, v47
	global_store_dwordx4 v[30:31], v[26:29], off
	s_nop 1
	v_mul_u32_u24_e32 v0, 0x1600, v0
	s_waitcnt lgkmcnt(0)
	v_cvt_pk_bf16_f32 v26, v124, v125
	v_lshlrev_b32_e32 v0, 1, v0
	s_waitcnt lgkmcnt(0)
	v_cvt_pk_bf16_f32 v27, v126, v127
	v_lshl_add_u64 v[24:25], v[24:25], 0, v[0:1]
	s_waitcnt lgkmcnt(0)
	v_cvt_pk_bf16_f32 v28, v128, v129
	s_waitcnt lgkmcnt(0)
	v_cvt_pk_bf16_f32 v29, v130, v131
	global_store_dwordx4 v[24:25], v[26:29], off
	s_nop 1
	s_waitcnt lgkmcnt(0)
	s_mov_b64 s[14:15], 0

; #define LAS __attribute__((address_space(3)))
; __device__ __forceinline__ unsigned cvt_pk_bf16(float lo, float hi) { unsigned r; asm volatile("v_cvt_pk_bf16_f32 %0, %1, %2" : "=v"(r) : "v"(lo), "v"(hi)); return r; }
;     ...
;     const int c = lane & 7;
; #pragma unroll
;     for (int j = 0; j < 4; ++j) { const int n = (lane >> 3) + 8 * j; const LAS float* s = scr + (8 * c) * 33 + n;
;         u32x4 o; o.x = cvt_pk_bf16(s[0 * 33], s[1 * 33]); o.y = cvt_pk_bf16(s[2 * 33], s[3 * 33]); o.z = cvt_pk_bf16(s[4 * 33], s[5 * 33]); o.w = cvt_pk_bf16(s[6 * 33], s[7 * 33]);
;         const int nn = n0 + n; const int orow = mode ? ((nn >> 7) * 256 + (nn & 127) + (mode == 2 ? 128 : 0)) : nn;
;         *(u32x4*)(WT + (size_t)orow * K + k0 + 8 * c) = o; }
;     asm volatile("s_waitcnt lgkmcnt(0)" ::: "memory");
.LBB0_936:
	s_waitcnt lgkmcnt(0)
	ds_read2_b32 v[100:101], v44 offset1:33
	ds_read2_b32 v[102:103], v44 offset0:66 offset1:99
	ds_read2_b32 v[104:105], v44 offset0:132 offset1:165
	ds_read2_b32 v[106:107], v44 offset0:198 offset1:231
	ds_read2_b32 v[108:109], v44 offset0:8 offset1:41
	ds_read2_b32 v[110:111], v44 offset0:74 offset1:107
	ds_read2_b32 v[112:113], v44 offset0:140 offset1:173
	ds_read2_b32 v[114:115], v44 offset0:206 offset1:239
	ds_read2_b32 v[116:117], v44 offset0:16 offset1:49
	ds_read2_b32 v[118:119], v44 offset0:82 offset1:115
	ds_read2_b32 v[120:121], v44 offset0:148 offset1:181
	ds_read2_b32 v[122:123], v44 offset0:214 offset1:247
	ds_read2_b32 v[124:125], v44 offset0:24 offset1:57
	ds_read2_b32 v[126:127], v44 offset0:90 offset1:123
	ds_read2_b32 v[128:129], v44 offset0:156 offset1:189
	ds_read2_b32 v[130:131], v44 offset0:222 offset1:255
	s_waitcnt lgkmcnt(0)
	s_lshl_b32 s14, s17, 6
	s_and_b32 s14, s14, 0x3f00
	s_and_b32 s11, s11, 0x60
	s_bitset1_b32 s14, 7
	s_and_b32 s15, 0xffff, s16
	s_waitcnt lgkmcnt(0)
	v_cvt_pk_bf16_f32 v26, v100, v101
	v_or_b32_e32 v0, s11, v3
	s_lshl_b32 s8, s15, 1
	s_waitcnt lgkmcnt(0)
	v_cvt_pk_bf16_f32 v27, v102, v103
	v_or_b32_e32 v0, s14, v0
	v_lshl_add_u64 v[24:25], v[8:9], 0, s[8:9]
	s_waitcnt lgkmcnt(0)
	v_cvt_pk_bf16_f32 v28, v104, v105
	v_lshlrev_b32_e32 v0, 12, v0
	s_waitcnt lgkmcnt(0)
	v_cvt_pk_bf16_f32 v29, v106, v107
	v_lshl_add_u64 v[30:31], v[24:25], 0, v[0:1]
	global_store_dwordx4 v[30:31], v[26:29], off
	s_nop 1
	v_or_b32_e32 v0, s11, v45
	s_waitcnt lgkmcnt(0)
	v_cvt_pk_bf16_f32 v26, v108, v109
	s_waitcnt lgkmcnt(0)
	v_cvt_pk_bf16_f32 v27, v110, v111
	v_or_b32_e32 v0, s14, v0
	s_waitcnt lgkmcnt(0)
	v_cvt_pk_bf16_f32 v28, v112, v113
	v_lshlrev_b32_e32 v0, 12, v0
	s_waitcnt lgkmcnt(0)
	v_cvt_pk_bf16_f32 v29, v114, v115
	v_lshl_add_u64 v[30:31], v[24:25], 0, v[0:1]
	global_store_dwordx4 v[30:31], v[26:29], off
	s_nop 1
	v_or_b32_e32 v0, s11, v46
	s_waitcnt lgkmcnt(0)
	v_cvt_pk_bf16_f32 v26, v116, v117
	s_waitcnt lgkmcnt(0)
	v_cvt_pk_bf16_f32 v27, v118, v119
	v_or_b32_e32 v0, s14, v0
	s_waitcnt lgkmcnt(0)
	v_cvt_pk_bf16_f32 v28, v120, v121
	v_lshlrev_b32_e32 v0, 12, v0
	s_waitcnt lgkmcnt(0)
	v_cvt_pk_bf16_f32 v29, v122, v123
	v_lshl_add_u64 v[30:31], v[24:25], 0, v[0:1]
	v_or_b32_e32 v0, s11, v47
	global_store_dwordx4 v[30:31], v[26:29], off
	s_nop 1
	v_or_b32_e32 v0, s14, v0
	s_waitcnt lgkmcnt(0)
	v_cvt_pk_bf16_f32 v26, v124, v125
	v_lshlrev_b32_e32 v0, 12, v0
	s_waitcnt lgkmcnt(0)
	v_cvt_pk_bf16_f32 v27, v126, v127
	v_lshl_add_u64 v[24:25], v[24:25], 0, v[0:1]
	s_waitcnt lgkmcnt(0)
	v_cvt_pk_bf16_f32 v28, v128, v129
	s_waitcnt lgkmcnt(0)
	v_cvt_pk_bf16_f32 v29, v130, v131
	global_store_dwordx4 v[24:25], v[26:29], off
	s_nop 1
	s_waitcnt lgkmcnt(0)

; #define LAS __attribute__((address_space(3)))
; __device__ __forceinline__ unsigned cvt_pk_bf16(float lo, float hi) { unsigned r; asm volatile("v_cvt_pk_bf16_f32 %0, %1, %2" : "=v"(r) : "v"(lo), "v"(hi)); return r; }
;     ...
;     const int c = lane & 7;
; #pragma unroll
;     for (int j = 0; j < 4; ++j) { const int n = (lane >> 3) + 8 * j; const LAS float* s = scr + (8 * c) * 33 + n;
;         u32x4 o; o.x = cvt_pk_bf16(s[0 * 33], s[1 * 33]); o.y = cvt_pk_bf16(s[2 * 33], s[3 * 33]); o.z = cvt_pk_bf16(s[4 * 33], s[5 * 33]); o.w = cvt_pk_bf16(s[6 * 33], s[7 * 33]);
;         const int nn = n0 + n; const int orow = mode ? ((nn >> 7) * 256 + (nn & 127) + (mode == 2 ? 128 : 0)) : nn;
;         *(u32x4*)(WT + (size_t)orow * K + k0 + 8 * c) = o; }
;     asm volatile("s_waitcnt lgkmcnt(0)" ::: "memory");
.LBB0_957:
	s_waitcnt lgkmcnt(0)
	ds_read2_b32 v[100:101], v44 offset1:33
	ds_read2_b32 v[102:103], v44 offset0:66 offset1:99
	ds_read2_b32 v[104:105], v44 offset0:132 offset1:165
	ds_read2_b32 v[106:107], v44 offset0:198 offset1:231
	ds_read2_b32 v[108:109], v44 offset0:8 offset1:41
	ds_read2_b32 v[110:111], v44 offset0:74 offset1:107
	ds_read2_b32 v[112:113], v44 offset0:140 offset1:173
	ds_read2_b32 v[114:115], v44 offset0:206 offset1:239
	ds_read2_b32 v[116:117], v44 offset0:16 offset1:49
	ds_read2_b32 v[118:119], v44 offset0:82 offset1:115
	ds_read2_b32 v[120:121], v44 offset0:148 offset1:181
	ds_read2_b32 v[122:123], v44 offset0:214 offset1:247
	ds_read2_b32 v[124:125], v44 offset0:24 offset1:57
	ds_read2_b32 v[126:127], v44 offset0:90 offset1:123
	ds_read2_b32 v[128:129], v44 offset0:156 offset1:189
	ds_read2_b32 v[130:131], v44 offset0:222 offset1:255
	s_waitcnt lgkmcnt(0)
	s_lshl_b32 s14, s17, 6
	s_and_b32 s11, s11, 0x60
	s_and_b32 s14, s14, 0x3f00
	s_and_b32 s15, 0xffff, s16
	s_waitcnt lgkmcnt(0)
	v_cvt_pk_bf16_f32 v26, v100, v101
	v_or_b32_e32 v0, s11, v3
	s_lshl_b32 s8, s15, 1
	s_waitcnt lgkmcnt(0)
	v_cvt_pk_bf16_f32 v27, v102, v103
	v_or_b32_e32 v0, s14, v0
	v_lshl_add_u64 v[24:25], v[8:9], 0, s[8:9]
	s_waitcnt lgkmcnt(0)
	v_cvt_pk_bf16_f32 v28, v104, v105
	v_lshlrev_b32_e32 v0, 12, v0
	s_waitcnt lgkmcnt(0)
	v_cvt_pk_bf16_f32 v29, v106, v107
	v_lshl_add_u64 v[30:31], v[24:25], 0, v[0:1]
	global_store_dwordx4 v[30:31], v[26:29], off
	s_nop 1
	v_or_b32_e32 v0, s11, v45
	s_waitcnt lgkmcnt(0)
	v_cvt_pk_bf16_f32 v26, v108, v109
	s_waitcnt lgkmcnt(0)
	v_cvt_pk_bf16_f32 v27, v110, v111
	v_or_b32_e32 v0, s14, v0
	s_waitcnt lgkmcnt(0)
	v_cvt_pk_bf16_f32 v28, v112, v113
	v_lshlrev_b32_e32 v0, 12, v0
	s_waitcnt lgkmcnt(0)
	v_cvt_pk_bf16_f32 v29, v114, v115
	v_lshl_add_u64 v[30:31], v[24:25], 0, v[0:1]
	global_store_dwordx4 v[30:31], v[26:29], off
	s_nop 1
	v_or_b32_e32 v0, s11, v46
	s_waitcnt lgkmcnt(0)
	v_cvt_pk_bf16_f32 v26, v116, v117
	s_waitcnt lgkmcnt(0)
	v_cvt_pk_bf16_f32 v27, v118, v119
	v_or_b32_e32 v0, s14, v0
	s_waitcnt lgkmcnt(0)
	v_cvt_pk_bf16_f32 v28, v120, v121
	v_lshlrev_b32_e32 v0, 12, v0
	s_waitcnt lgkmcnt(0)
	v_cvt_pk_bf16_f32 v29, v122, v123
	v_lshl_add_u64 v[30:31], v[24:25], 0, v[0:1]
	v_or_b32_e32 v0, s11, v47
	global_store_dwordx4 v[30:31], v[26:29], off
	s_nop 1
	v_or_b32_e32 v0, s14, v0
	s_waitcnt lgkmcnt(0)
	v_cvt_pk_bf16_f32 v26, v124, v125
	v_lshlrev_b32_e32 v0, 12, v0
	s_waitcnt lgkmcnt(0)
	v_cvt_pk_bf16_f32 v27, v126, v127
	v_lshl_add_u64 v[24:25], v[24:25], 0, v[0:1]
	s_waitcnt lgkmcnt(0)
	v_cvt_pk_bf16_f32 v28, v128, v129
	s_waitcnt lgkmcnt(0)
	v_cvt_pk_bf16_f32 v29, v130, v131
	global_store_dwordx4 v[24:25], v[26:29], off
	s_nop 1
	s_waitcnt lgkmcnt(0)

;     ...
; #pragma unroll 8
;     for (int i = 0; i < 32; ++i) { const int kk = 2 * i + (lane >> 5); float v = __builtin_nontemporal_load(W + (size_t)(k0 + kk) * N + n0 + (lane & 31)); if (gain) v *= gain[k0 + kk]; scr[kk * 33 + (lane & 31)] = v; }
;     asm volatile("s_waitcnt lgkmcnt(0)" ::: "memory");
.LBB0_961:
	v_lshl_add_u64 v[164:165], v[38:39], 0, s[14:15]
	global_load_dword v100, v[164:165], off nt
	v_lshl_add_u64 v[164:165], v[36:37], 0, s[14:15]
	global_load_dword v101, v[164:165], off nt
	v_lshl_add_u64 v[164:165], v[34:35], 0, s[14:15]
	global_load_dword v102, v[164:165], off nt
	v_lshl_add_u64 v[164:165], v[32:33], 0, s[14:15]
	global_load_dword v103, v[164:165], off nt
	v_lshl_add_u64 v[164:165], v[30:31], 0, s[14:15]
	global_load_dword v104, v[164:165], off nt
	v_lshl_add_u64 v[164:165], v[28:29], 0, s[14:15]
	global_load_dword v105, v[164:165], off nt
	v_lshl_add_u64 v[164:165], v[26:27], 0, s[14:15]
	global_load_dword v106, v[164:165], off nt
	v_lshl_add_u64 v[164:165], v[24:25], 0, s[14:15]
	global_load_dword v107, v[164:165], off nt
	s_add_u32 s14, s14, 0x20000
	s_addc_u32 s15, s15, 0
	v_lshl_add_u64 v[164:165], v[38:39], 0, s[14:15]
	global_load_dword v108, v[164:165], off nt
	v_lshl_add_u64 v[164:165], v[36:37], 0, s[14:15]
	global_load_dword v109, v[164:165], off nt
	v_lshl_add_u64 v[164:165], v[34:35], 0, s[14:15]
	global_load_dword v110, v[164:165], off nt
	v_lshl_add_u64 v[164:165], v[32:33], 0, s[14:15]
	global_load_dword v111, v[164:165], off nt
	v_lshl_add_u64 v[164:165], v[30:31], 0, s[14:15]
	global_load_dword v112, v[164:165], off nt
	v_lshl_add_u64 v[164:165], v[28:29], 0, s[14:15]
	global_load_dword v113, v[164:165], off nt
	v_lshl_add_u64 v[164:165], v[26:27], 0, s[14:15]
	global_load_dword v114, v[164:165], off nt
	v_lshl_add_u64 v[164:165], v[24:25], 0, s[14:15]
	global_load_dword v115, v[164:165], off nt
	s_add_u32 s14, s14, 0x20000
	s_addc_u32 s15, s15, 0
	v_lshl_add_u64 v[164:165], v[38:39], 0, s[14:15]
	global_load_dword v116, v[164:165], off nt
	v_lshl_add_u64 v[164:165], v[36:37], 0, s[14:15]
	global_load_dword v117, v[164:165], off nt
	v_lshl_add_u64 v[164:165], v[34:35], 0, s[14:15]
	global_load_dword v118, v[164:165], off nt
	v_lshl_add_u64 v[164:165], v[32:33], 0, s[14:15]
	global_load_dword v119, v[164:165], off nt
	v_lshl_add_u64 v[164:165], v[30:31], 0, s[14:15]
	global_load_dword v120, v[164:165], off nt
	v_lshl_add_u64 v[164:165], v[28:29], 0, s[14:15]
	global_load_dword v121, v[164:165], off nt
	v_lshl_add_u64 v[164:165], v[26:27], 0, s[14:15]
	global_load_dword v122, v[164:165], off nt
	v_lshl_add_u64 v[164:165], v[24:25], 0, s[14:15]
	global_load_dword v123, v[164:165], off nt
	s_add_u32 s14, s14, 0x20000
	s_addc_u32 s15, s15, 0
	v_lshl_add_u64 v[164:165], v[38:39], 0, s[14:15]
	global_load_dword v124, v[164:165], off nt
	v_lshl_add_u64 v[164:165], v[36:37], 0, s[14:15]
	global_load_dword v125, v[164:165], off nt
	v_lshl_add_u64 v[164:165], v[34:35], 0, s[14:15]
	global_load_dword v126, v[164:165], off nt
	v_lshl_add_u64 v[164:165], v[32:33], 0, s[14:15]
	global_load_dword v127, v[164:165], off nt
	v_lshl_add_u64 v[164:165], v[30:31], 0, s[14:15]
	global_load_dword v128, v[164:165], off nt
	v_lshl_add_u64 v[164:165], v[28:29], 0, s[14:15]
	global_load_dword v129, v[164:165], off nt
	v_lshl_add_u64 v[164:165], v[26:27], 0, s[14:15]
	global_load_dword v130, v[164:165], off nt
	v_lshl_add_u64 v[164:165], v[24:25], 0, s[14:15]
	global_load_dword v131, v[164:165], off nt
	s_add_u32 s14, s14, 0x20000
	s_addc_u32 s15, s15, 0
	s_waitcnt vmcnt(24)
	ds_write_b32 v0, v100
	ds_write_b32 v0, v101 offset:264
	ds_write_b32 v0, v102 offset:528
	ds_write_b32 v0, v103 offset:792
	ds_write_b32 v0, v104 offset:1056
	ds_write_b32 v0, v105 offset:1320
	ds_write_b32 v0, v106 offset:1584
	ds_write_b32 v0, v107 offset:1848
	s_waitcnt vmcnt(16)
; #define LAS __attribute__((address_space(3)))
; __device__ __forceinline__ unsigned cvt_pk_bf16(float lo, float hi) { unsigned r; asm volatile("v_cvt_pk_bf16_f32 %0, %1, %2" : "=v"(r) : "v"(lo), "v"(hi)); return r; }
;     ...
;     for (int i = 0; i < 32; ++i) { const int kk = 2 * i + (lane >> 5); float v = __builtin_nontemporal_load(W + (size_t)(k0 + kk) * N + n0 + (lane & 31)); if (gain) v *= gain[k0 + kk]; scr[kk * 33 + (lane & 31)] = v; }
;     asm volatile("s_waitcnt lgkmcnt(0)" ::: "memory");
;     const int c = lane & 7;
; #pragma unroll
;     for (int j = 0; j < 4; ++j) { const int n = (lane >> 3) + 8 * j; const LAS float* s = scr + (8 * c) * 33 + n;
;         u32x4 o; o.x = cvt_pk_bf16(s[0 * 33], s[1 * 33]); o.y = cvt_pk_bf16(s[2 * 33], s[3 * 33]); o.z = cvt_pk_bf16(s[4 * 33], s[5 * 33]); o.w = cvt_pk_bf16(s[6 * 33], s[7 * 33]);
;         const int nn = n0 + n; const int orow = mode ? ((nn >> 7) * 256 + (nn & 127) + (mode == 2 ? 128 : 0)) : nn;
;         *(u32x4*)(WT + (size_t)orow * K + k0 + 8 * c) = o; }
	ds_write_b32 v0, v108 offset:2112
	ds_write_b32 v0, v109 offset:2376
	ds_write_b32 v0, v110 offset:2640
	ds_write_b32 v0, v111 offset:2904
	ds_write_b32 v0, v112 offset:3168
	ds_write_b32 v0, v113 offset:3432
	ds_write_b32 v0, v114 offset:3696
	ds_write_b32 v0, v115 offset:3960
	s_waitcnt vmcnt(8)
	ds_write_b32 v0, v116 offset:4224
	ds_write_b32 v0, v117 offset:4488
	ds_write_b32 v0, v118 offset:4752
	ds_write_b32 v0, v119 offset:5016
	ds_write_b32 v0, v120 offset:5280
	ds_write_b32 v0, v121 offset:5544
	ds_write_b32 v0, v122 offset:5808
	ds_write_b32 v0, v123 offset:6072
	s_waitcnt vmcnt(0)
	ds_write_b32 v0, v124 offset:6336
	ds_write_b32 v0, v125 offset:6600
	ds_write_b32 v0, v126 offset:6864
	ds_write_b32 v0, v127 offset:7128
	ds_write_b32 v0, v128 offset:7392
	ds_write_b32 v0, v129 offset:7656
	ds_write_b32 v0, v130 offset:7920
	ds_write_b32 v0, v131 offset:8184
	v_add_u32_e32 v0, 0x2100, v0
	s_add_i32 s10, s3, 0xe800
	s_waitcnt lgkmcnt(0)
	ds_read2_b32 v[100:101], v44 offset1:33
	ds_read2_b32 v[102:103], v44 offset0:66 offset1:99
	ds_read2_b32 v[104:105], v44 offset0:132 offset1:165
	ds_read2_b32 v[106:107], v44 offset0:198 offset1:231
	ds_read2_b32 v[108:109], v44 offset0:8 offset1:41
	ds_read2_b32 v[110:111], v44 offset0:74 offset1:107
	ds_read2_b32 v[112:113], v44 offset0:140 offset1:173
	ds_read2_b32 v[114:115], v44 offset0:206 offset1:239
	ds_read2_b32 v[116:117], v44 offset0:16 offset1:49
	ds_read2_b32 v[118:119], v44 offset0:82 offset1:115
	ds_read2_b32 v[120:121], v44 offset0:148 offset1:181
	ds_read2_b32 v[122:123], v44 offset0:214 offset1:247
	ds_read2_b32 v[124:125], v44 offset0:24 offset1:57
	ds_read2_b32 v[126:127], v44 offset0:90 offset1:123
	ds_read2_b32 v[128:129], v44 offset0:156 offset1:189
	ds_read2_b32 v[130:131], v44 offset0:222 offset1:255
	s_waitcnt lgkmcnt(0)
	s_and_b32 s11, s10, 0xffc0
	s_lshl_b32 s10, s3, 5
	s_and_b32 s10, s10, 0x7e0
	s_waitcnt lgkmcnt(0)
	v_cvt_pk_bf16_f32 v24, v100, v101
	s_lshl_b32 s8, s11, 1
	s_waitcnt lgkmcnt(0)
	v_cvt_pk_bf16_f32 v25, v102, v103
	v_or_b32_e32 v0, s10, v3
	v_lshl_add_u64 v[28:29], v[10:11], 0, s[8:9]
	s_waitcnt lgkmcnt(0)
	v_cvt_pk_bf16_f32 v26, v104, v105
	v_lshlrev_b32_e32 v0, 12, v0
	s_waitcnt lgkmcnt(0)
	v_cvt_pk_bf16_f32 v27, v106, v107
	v_lshl_add_u64 v[30:31], v[28:29], 0, v[0:1]
	global_store_dwordx4 v[30:31], v[24:27], off
	s_nop 1
	v_or_b32_e32 v0, s10, v45
	s_waitcnt lgkmcnt(0)
	v_cvt_pk_bf16_f32 v24, v108, v109
	s_waitcnt lgkmcnt(0)
	v_cvt_pk_bf16_f32 v25, v110, v111
	s_waitcnt lgkmcnt(0)
	v_cvt_pk_bf16_f32 v26, v112, v113
	v_lshlrev_b32_e32 v0, 12, v0
	s_waitcnt lgkmcnt(0)
	v_cvt_pk_bf16_f32 v27, v114, v115
	v_lshl_add_u64 v[30:31], v[28:29], 0, v[0:1]
	global_store_dwordx4 v[30:31], v[24:27], off
	s_nop 1
	v_or_b32_e32 v0, s10, v46
	s_waitcnt lgkmcnt(0)
	v_cvt_pk_bf16_f32 v24, v116, v117
	s_waitcnt lgkmcnt(0)
	v_cvt_pk_bf16_f32 v25, v118, v119
	s_waitcnt lgkmcnt(0)
	v_cvt_pk_bf16_f32 v26, v120, v121
	v_lshlrev_b32_e32 v0, 12, v0
	s_waitcnt lgkmcnt(0)
	v_cvt_pk_bf16_f32 v27, v122, v123
	v_lshl_add_u64 v[30:31], v[28:29], 0, v[0:1]
	global_store_dwordx4 v[30:31], v[24:27], off
	s_nop 1
	v_or_b32_e32 v0, s10, v47
	s_waitcnt lgkmcnt(0)
	v_cvt_pk_bf16_f32 v24, v124, v125
	v_lshlrev_b32_e32 v0, 12, v0
	s_waitcnt lgkmcnt(0)
	v_cvt_pk_bf16_f32 v25, v126, v127
	v_lshl_add_u64 v[28:29], v[28:29], 0, v[0:1]
	s_waitcnt lgkmcnt(0)
	v_cvt_pk_bf16_f32 v26, v128, v129
	s_waitcnt lgkmcnt(0)
	v_cvt_pk_bf16_f32 v27, v130, v131
	global_store_dwordx4 v[28:29], v[24:27], off
	s_nop 1
	s_waitcnt lgkmcnt(0)
